# GEMM loops: the leading half-workgroup skips the pre-barrier LDS wait (only the trailing half's reads are restaged right after the barrier)
# baseline (speedup 1.0000x reference)
.LBB0_89:
	v_readfirstlane_b32 s96, v211
	s_lshr_b32 s96, s96, 8
	v_mov_b32_e32 v138, v211
	s_mov_b32 s6, s74
	s_mov_b32 s8, s94
	v_readlane_b32 s1, v255, 31
	s_mov_b64 s[12:13], s[92:93]
	v_mov_b32_e32 v9, v211
	s_cmpk_gt_i32 s6, 0x2ff
	v_readfirstlane_b32 s0, v138
	v_readfirstlane_b32 s16, v9
	s_cbranch_scc1 .LBB0_105
	v_lshlrev_b32_e32 v0, 4, v9
	v_add_u32_e32 v1, 0x2000, v0
	v_ashrrev_i32_e32 v2, 31, v1
	v_lshrrev_b32_e32 v2, 22, v2
	v_add_u32_e32 v2, v1, v2
	v_ashrrev_i32_e32 v8, 10, v2
	v_mul_i32_i24_e32 v2, 0x400, v8
	v_sub_u32_e32 v1, v1, v2
	v_lshrrev_b32_e32 v2, 4, v1
	v_bitop3_b32 v1, v2, v1, 32 bitop3:0x6c
	v_ashrrev_i32_e32 v2, 31, v1
	v_lshrrev_b32_e32 v2, 26, v2
	v_add_u32_e32 v2, v1, v2
	v_lshlrev_b32_e32 v3, 3, v8
	v_ashrrev_i32_e32 v10, 6, v2
	v_and_b32_e32 v3, -16, v3
	v_add_u32_e32 v3, v10, v3
	v_and_b32_e32 v4, 3, v10
	s_mov_b32 s4, 0x1fffe0
	v_lshrrev_b32_e32 v5, 2, v3
	v_lshlrev_b32_e32 v6, 1, v3
	v_and_b32_e32 v2, 0xc0, v2
	v_and_or_b32 v4, v3, s4, v4
	v_and_b32_e32 v5, 4, v5
	v_and_b32_e32 v6, 24, v6
	v_sub_u32_e32 v1, v1, v2
	v_or3_b32 v4, v4, v5, v6
	v_lshlrev_b32_e32 v5, 5, v8
	v_ashrrev_i16_sdwa v1, v225, sext(v1) dst_sel:DWORD dst_unused:UNUSED_PAD src0_sel:DWORD src1_sel:BYTE_0
	v_and_b32_e32 v5, 32, v5
	v_bfe_i32 v11, v1, 0, 16
	v_add_lshl_u32 v1, v5, v11, 1
	v_lshl_add_u32 v128, v4, 11, v1
	v_lshl_add_u32 v130, v3, 11, v1
	v_bfe_i32 v1, v9, 27, 1
	v_lshrrev_b32_e32 v1, 22, v1
	v_add_u32_e32 v1, v0, v1
	v_and_b32_e32 v1, 0xfffffc00, v1
	v_sub_u32_e32 v0, v0, v1
	v_lshrrev_b32_e32 v1, 4, v0
	v_ashrrev_i32_e32 v2, 31, v9
	v_bitop3_b32 v0, v1, v0, 32 bitop3:0x6c
	v_lshrrev_b32_e32 v2, 26, v2
	v_ashrrev_i32_e32 v1, 31, v0
	v_add_u32_e32 v2, v9, v2
	s_add_u32 s2, s12, 0xae00000
	v_lshrrev_b32_e32 v1, 26, v1
	v_ashrrev_i32_e32 v13, 6, v2
	s_addc_u32 s3, s13, 0
	v_add_u32_e32 v1, v0, v1
	v_lshlrev_b32_e32 v2, 3, v13
	s_add_u32 s7, s12, 0x200000
	v_ashrrev_i32_e32 v12, 6, v1
	v_and_b32_e32 v2, -16, v2
	s_addc_u32 s9, s13, 0
	v_add_u32_e32 v2, v12, v2
	v_and_b32_e32 v3, 3, v12
	s_ashr_i32 s21, s6, 31
	v_and_or_b32 v3, v2, s4, v3
	s_lshr_b32 s4, s21, 29
	s_add_i32 s4, s6, s4
	s_ashr_i32 s18, s16, 6
	s_ashr_i32 s14, s4, 3
	s_and_b32 s4, s4, -8
	s_ashr_i32 s17, s16, 8
	s_lshl_b32 s20, s18, 10
	s_sub_i32 s4, s6, s4
	s_cmp_lt_i32 s4, 0
	s_movk_i32 s15, 0x61
	s_cselect_b32 s15, s15, 0x60
	s_mul_i32 s4, s4, s15
	s_add_i32 s4, s4, s14
	s_mul_hi_i32 s14, s4, 0x2aaaaaab
	s_lshr_b32 s15, s14, 31
	s_ashr_i32 s14, s14, 4
	s_add_i32 s14, s14, s15
	s_lshl_b32 s15, s14, 3
	s_mulk_i32 s14, 0x60
	s_sub_i32 s14, s4, s14
	s_bfe_i32 s4, s14, 0x80000
	s_bfe_u32 s4, s4, 0x3000c
	s_add_i32 s19, s14, s4
	s_bfe_i32 s4, s19, 0x80000
	s_and_b32 s19, s19, 0xf8
	s_sub_i32 s14, s14, s19
	s_sext_i32_i16 s4, s4
	s_sext_i32_i8 s14, s14
	v_lshrrev_b32_e32 v4, 2, v2
	v_lshlrev_b32_e32 v5, 1, v2
	v_and_b32_e32 v1, 0xc0, v1
	s_lshr_b32 s4, s4, 3
	s_add_i32 s46, s15, s14
	v_and_b32_e32 v4, 4, v4
	v_and_b32_e32 v5, 24, v5
	v_sub_u32_e32 v0, v0, v1
	s_ashr_i32 s47, s46, 31
	s_bfe_i64 s[22:23], s[4:5], 0x100000
	v_or3_b32 v3, v3, v4, v5
	v_lshlrev_b32_e32 v4, 5, v13
	v_ashrrev_i16_sdwa v0, v225, sext(v0) dst_sel:DWORD dst_unused:UNUSED_PAD src0_sel:DWORD src1_sel:BYTE_0
	s_lshl_b64 s[14:15], s[46:47], 19
	s_lshl_b64 s[22:23], s[22:23], 19
	v_and_b32_e32 v4, 32, v4
	v_bfe_i32 v14, v0, 0, 16
	s_add_u32 s50, s7, s22
	v_add_lshl_u32 v0, v4, v14, 1
	s_addc_u32 s51, s9, s23
	s_add_i32 s22, s20, 0
	v_lshl_add_u32 v196, v3, 11, v0
	s_add_i32 m0, s22, 0x10000
	v_lshl_add_u32 v132, v2, 11, v0
	global_load_lds_dwordx4 v196, s[50:51]
	s_add_i32 m0, s22, 0x12000
	s_add_u32 s24, s50, 0x40000
	global_load_lds_dwordx4 v128, s[50:51]
	s_addc_u32 s25, s51, 0
	s_add_i32 m0, s22, 0x14000
	v_mov_b32_e32 v129, v197
	global_load_lds_dwordx4 v196, s[24:25]
	s_add_i32 m0, s22, 0x16000
	s_add_u32 s48, s2, s14
	s_addc_u32 s49, s3, s15
	s_add_i32 s23, s22, 0x2000
	global_load_lds_dwordx4 v128, s[24:25]
	s_mov_b32 m0, s22
	s_add_u32 s14, s48, 0x40000
	global_load_lds_dwordx4 v132, s[48:49]
	s_mov_b32 m0, s23
	s_addc_u32 s15, s49, 0
	s_add_i32 s24, s22, 0x4000
	global_load_lds_dwordx4 v130, s[48:49]
	s_mov_b32 m0, s24
	s_add_i32 s25, s22, 0x6000
	global_load_lds_dwordx4 v132, s[14:15]
	s_mov_b32 m0, s25
	v_mov_b32_e32 v133, v197
	global_load_lds_dwordx4 v130, s[14:15]
	v_mov_b32_e32 v131, v197
	s_cmp_eq_u32 s17, 1
	v_lshl_add_u64 v[6:7], s[50:51], 0, v[196:197]
	v_lshl_add_u64 v[4:5], s[50:51], 0, v[128:129]
	v_lshl_add_u64 v[0:1], s[48:49], 0, v[132:133]
	s_cselect_b64 s[14:15], -1, 0
	s_cmp_lg_u32 s17, 1
	v_lshl_add_u64 v[2:3], s[48:49], 0, v[130:131]
	s_cbranch_scc1 .LBB0_92
	s_barrier

.LBB0_98:
	s_add_u32 s41, s48, 0xfffc0080
	s_addc_u32 s47, s49, -1
	s_add_i32 s54, 0, 0x10000
	s_cmp_eq_u32 s37, 12
	s_cselect_b32 s53, s30, s47
	s_cselect_b32 s52, s31, s41
	v_add_u32_e32 v143, s54, v140
	s_cselect_b32 s51, s19, s36
	s_cselect_b32 s50, s34, s35
	s_add_i32 s41, 0, 0x14000
	ds_read_b128 v[144:147], v143
	ds_read_b128 v[148:151], v143 offset:1024
	ds_read_b128 v[152:155], v143 offset:2048
	ds_read_b128 v[156:159], v143 offset:3072
	v_add_u32_e32 v143, s41, v140
	ds_read_b128 v[164:167], v143
	ds_read_b128 v[168:171], v143 offset:1024
	ds_read_b128 v[172:175], v143 offset:2048
	ds_read_b128 v[176:179], v143 offset:3072
	v_lshl_add_u64 v[204:205], s[48:49], 0, v[134:135]
	s_add_i32 m0, s22, 0xc000
	ds_read_b128 v[180:183], v142
	ds_read_b128 v[184:187], v142 offset:1024
	ds_read_b128 v[188:191], v142 offset:2048
	ds_read_b128 v[192:195], v142 offset:3072
	ds_read_b128 v[212:215], v142 offset:4096
	ds_read_b128 v[216:219], v142 offset:5120
	ds_read_b128 v[220:223], v142 offset:6144
	ds_read_b128 v[232:235], v142 offset:7168
	global_load_lds_dwordx4 v[204:205], off
	v_lshl_add_u64 v[204:205], s[48:49], 0, v[136:137]
	s_add_i32 m0, s22, 0xe000
	s_nop 0
	global_load_lds_dwordx4 v[204:205], off
	s_waitcnt vmcnt(8)
	s_cmp_eq_u32 s96, 0
	s_cbranch_scc1 .Lgl0
	s_waitcnt lgkmcnt(0)
.Lgl0:
	s_barrier
	s_waitcnt lgkmcnt(0)
	v_mfma_f32_16x16x32_bf16 v[124:127], v[144:147], v[180:183], v[124:127]
	v_mfma_f32_16x16x32_bf16 v[120:123], v[152:155], v[180:183], v[120:123]
	v_mfma_f32_16x16x32_bf16 v[116:119], v[144:147], v[188:191], v[116:119]
	v_mfma_f32_16x16x32_bf16 v[108:111], v[152:155], v[188:191], v[108:111]
	v_mfma_f32_16x16x32_bf16 v[100:103], v[144:147], v[212:215], v[100:103]
	v_mfma_f32_16x16x32_bf16 v[92:95], v[152:155], v[212:215], v[92:95]
	v_mfma_f32_16x16x32_bf16 v[84:87], v[144:147], v[220:223], v[84:87]
	v_mfma_f32_16x16x32_bf16 v[76:79], v[152:155], v[220:223], v[76:79]
	v_mfma_f32_16x16x32_bf16 v[124:127], v[148:151], v[184:187], v[124:127]
	v_mfma_f32_16x16x32_bf16 v[120:123], v[156:159], v[184:187], v[120:123]
	v_mfma_f32_16x16x32_bf16 v[116:119], v[148:151], v[192:195], v[116:119]
	v_mfma_f32_16x16x32_bf16 v[108:111], v[156:159], v[192:195], v[108:111]
	v_mfma_f32_16x16x32_bf16 v[100:103], v[148:151], v[216:219], v[100:103]
	v_mfma_f32_16x16x32_bf16 v[92:95], v[156:159], v[216:219], v[92:95]
	v_mfma_f32_16x16x32_bf16 v[84:87], v[148:151], v[232:235], v[84:87]
	v_mfma_f32_16x16x32_bf16 v[76:79], v[156:159], v[232:235], v[76:79]
	v_mfma_f32_16x16x32_bf16 v[112:115], v[164:167], v[180:183], v[112:115]
	v_mfma_f32_16x16x32_bf16 v[104:107], v[172:175], v[180:183], v[104:107]
	v_mfma_f32_16x16x32_bf16 v[96:99], v[164:167], v[188:191], v[96:99]
	v_mfma_f32_16x16x32_bf16 v[88:91], v[172:175], v[188:191], v[88:91]
	v_mfma_f32_16x16x32_bf16 v[80:83], v[164:167], v[212:215], v[80:83]
	v_mfma_f32_16x16x32_bf16 v[72:75], v[172:175], v[212:215], v[72:75]
	v_mfma_f32_16x16x32_bf16 v[68:71], v[164:167], v[220:223], v[68:71]
	v_mfma_f32_16x16x32_bf16 v[64:67], v[172:175], v[220:223], v[64:67]
	v_mfma_f32_16x16x32_bf16 v[112:115], v[168:171], v[184:187], v[112:115]
	v_mfma_f32_16x16x32_bf16 v[104:107], v[176:179], v[184:187], v[104:107]
	v_mfma_f32_16x16x32_bf16 v[96:99], v[168:171], v[192:195], v[96:99]
	v_mfma_f32_16x16x32_bf16 v[88:91], v[176:179], v[192:195], v[88:91]
	v_mfma_f32_16x16x32_bf16 v[80:83], v[168:171], v[216:219], v[80:83]
	v_mfma_f32_16x16x32_bf16 v[72:75], v[176:179], v[216:219], v[72:75]
	v_mfma_f32_16x16x32_bf16 v[68:71], v[168:171], v[232:235], v[68:71]
	v_mfma_f32_16x16x32_bf16 v[64:67], v[176:179], v[232:235], v[64:67]
	s_barrier
	s_add_i32 s47, s54, s20
	v_lshl_add_u64 v[204:205], s[50:51], 0, v[196:197]
	s_mov_b32 m0, s47
	ds_read_b128 v[180:183], v142 offset:16384
	ds_read_b128 v[184:187], v142 offset:17408
	ds_read_b128 v[188:191], v142 offset:18432
	ds_read_b128 v[192:195], v142 offset:19456
	ds_read_b128 v[212:215], v142 offset:20480
	ds_read_b128 v[216:219], v142 offset:21504
	ds_read_b128 v[220:223], v142 offset:22528
	ds_read_b128 v[232:235], v142 offset:23552
	global_load_lds_dwordx4 v[204:205], off
	s_add_i32 m0, s47, 0x2000
	s_add_u32 s54, s50, 0x40000
	v_lshl_add_u64 v[206:207], s[50:51], 0, v[128:129]
	s_addc_u32 s55, s51, 0
	s_add_i32 s41, s41, s20
	global_load_lds_dwordx4 v[206:207], off
	v_lshl_add_u64 v[236:237], s[54:55], 0, v[196:197]
	s_mov_b32 m0, s41
	v_lshl_add_u64 v[238:239], s[52:53], 0, v[130:131]
	global_load_lds_dwordx4 v[236:237], off
	v_lshl_add_u64 v[236:237], s[54:55], 0, v[128:129]
	s_add_i32 m0, s41, 0x2000
	s_nop 0
	global_load_lds_dwordx4 v[236:237], off
	v_lshl_add_u64 v[236:237], s[52:53], 0, v[132:133]
	s_mov_b32 m0, s22
	s_nop 0
	global_load_lds_dwordx4 v[236:237], off
	s_mov_b32 m0, s23
	s_nop 0
	global_load_lds_dwordx4 v[238:239], off
	s_waitcnt vmcnt(8)
	s_cmp_eq_u32 s96, 0
	s_cbranch_scc1 .Lgl1
	s_waitcnt lgkmcnt(0)
.Lgl1:
	s_barrier
	s_waitcnt lgkmcnt(0)
	v_mfma_f32_16x16x32_bf16 v[60:63], v[144:147], v[180:183], v[60:63]
	v_mfma_f32_16x16x32_bf16 v[56:59], v[152:155], v[180:183], v[56:59]
	v_mfma_f32_16x16x32_bf16 v[52:55], v[144:147], v[188:191], v[52:55]
	v_mfma_f32_16x16x32_bf16 v[44:47], v[152:155], v[188:191], v[44:47]
	v_mfma_f32_16x16x32_bf16 v[36:39], v[144:147], v[212:215], v[36:39]
	v_mfma_f32_16x16x32_bf16 v[28:31], v[152:155], v[212:215], v[28:31]
	v_mfma_f32_16x16x32_bf16 v[20:23], v[144:147], v[220:223], v[20:23]
	v_mfma_f32_16x16x32_bf16 v[12:15], v[152:155], v[220:223], v[12:15]
	v_mfma_f32_16x16x32_bf16 v[60:63], v[148:151], v[184:187], v[60:63]
	v_mfma_f32_16x16x32_bf16 v[56:59], v[156:159], v[184:187], v[56:59]
	v_mfma_f32_16x16x32_bf16 v[52:55], v[148:151], v[192:195], v[52:55]
	v_mfma_f32_16x16x32_bf16 v[44:47], v[156:159], v[192:195], v[44:47]
	v_mfma_f32_16x16x32_bf16 v[36:39], v[148:151], v[216:219], v[36:39]
	v_mfma_f32_16x16x32_bf16 v[28:31], v[156:159], v[216:219], v[28:31]
	v_mfma_f32_16x16x32_bf16 v[20:23], v[148:151], v[232:235], v[20:23]
	v_mfma_f32_16x16x32_bf16 v[12:15], v[156:159], v[232:235], v[12:15]
	v_mfma_f32_16x16x32_bf16 v[48:51], v[164:167], v[180:183], v[48:51]
	v_mfma_f32_16x16x32_bf16 v[40:43], v[172:175], v[180:183], v[40:43]
	v_mfma_f32_16x16x32_bf16 v[32:35], v[164:167], v[188:191], v[32:35]
	v_mfma_f32_16x16x32_bf16 v[24:27], v[172:175], v[188:191], v[24:27]
	v_mfma_f32_16x16x32_bf16 v[16:19], v[164:167], v[212:215], v[16:19]
	v_mfma_f32_16x16x32_bf16 v[8:11], v[172:175], v[212:215], v[8:11]
	v_mfma_f32_16x16x32_bf16 v[4:7], v[164:167], v[220:223], v[4:7]
	v_mfma_f32_16x16x32_bf16 v[0:3], v[172:175], v[220:223], v[0:3]
	v_mfma_f32_16x16x32_bf16 v[48:51], v[168:171], v[184:187], v[48:51]
	v_mfma_f32_16x16x32_bf16 v[40:43], v[176:179], v[184:187], v[40:43]
	v_mfma_f32_16x16x32_bf16 v[32:35], v[168:171], v[192:195], v[32:35]
	v_mfma_f32_16x16x32_bf16 v[24:27], v[176:179], v[192:195], v[24:27]
	v_mfma_f32_16x16x32_bf16 v[16:19], v[168:171], v[216:219], v[16:19]
	v_mfma_f32_16x16x32_bf16 v[8:11], v[176:179], v[216:219], v[8:11]
	v_mfma_f32_16x16x32_bf16 v[4:7], v[168:171], v[232:235], v[4:7]
	v_mfma_f32_16x16x32_bf16 v[0:3], v[176:179], v[232:235], v[0:3]
	s_barrier
	s_add_i32 s41, 0, 0x18000
	v_add_u32_e32 v143, s41, v140
	s_add_i32 s47, 0, 0x1c000
	ds_read_b128 v[144:147], v143
	ds_read_b128 v[148:151], v143 offset:1024
	ds_read_b128 v[152:155], v143 offset:2048
	ds_read_b128 v[156:159], v143 offset:3072
	v_add_u32_e32 v143, s47, v140
	ds_read_b128 v[164:167], v143
	ds_read_b128 v[168:171], v143 offset:1024
	ds_read_b128 v[172:175], v143 offset:2048
	ds_read_b128 v[176:179], v143 offset:3072
	s_add_u32 s52, s52, 0x40000
	s_addc_u32 s53, s53, 0
	s_mov_b32 m0, s24
	v_lshl_add_u64 v[240:241], s[52:53], 0, v[132:133]
	ds_read_b128 v[180:183], v142 offset:32768
	ds_read_b128 v[184:187], v142 offset:33792
	ds_read_b128 v[188:191], v142 offset:34816
	ds_read_b128 v[192:195], v142 offset:35840
	ds_read_b128 v[212:215], v142 offset:36864
	ds_read_b128 v[216:219], v142 offset:37888
	ds_read_b128 v[220:223], v142 offset:38912
	ds_read_b128 v[232:235], v142 offset:39936
	global_load_lds_dwordx4 v[240:241], off
	v_lshl_add_u64 v[240:241], s[52:53], 0, v[130:131]
	s_mov_b32 m0, s25
	s_nop 0
	global_load_lds_dwordx4 v[240:241], off
	s_waitcnt vmcnt(8)
	s_cmp_eq_u32 s96, 0
	s_cbranch_scc1 .Lgl2
	s_waitcnt lgkmcnt(0)
.Lgl2:
	s_barrier
	s_waitcnt lgkmcnt(0)
	v_mfma_f32_16x16x32_bf16 v[124:127], v[144:147], v[180:183], v[124:127]
	v_mfma_f32_16x16x32_bf16 v[120:123], v[152:155], v[180:183], v[120:123]
	v_mfma_f32_16x16x32_bf16 v[116:119], v[144:147], v[188:191], v[116:119]
	v_mfma_f32_16x16x32_bf16 v[108:111], v[152:155], v[188:191], v[108:111]
	v_mfma_f32_16x16x32_bf16 v[100:103], v[144:147], v[212:215], v[100:103]
	v_mfma_f32_16x16x32_bf16 v[92:95], v[152:155], v[212:215], v[92:95]
	v_mfma_f32_16x16x32_bf16 v[84:87], v[144:147], v[220:223], v[84:87]
	v_mfma_f32_16x16x32_bf16 v[76:79], v[152:155], v[220:223], v[76:79]
	v_mfma_f32_16x16x32_bf16 v[124:127], v[148:151], v[184:187], v[124:127]
	v_mfma_f32_16x16x32_bf16 v[120:123], v[156:159], v[184:187], v[120:123]
	v_mfma_f32_16x16x32_bf16 v[116:119], v[148:151], v[192:195], v[116:119]
	v_mfma_f32_16x16x32_bf16 v[108:111], v[156:159], v[192:195], v[108:111]
	v_mfma_f32_16x16x32_bf16 v[100:103], v[148:151], v[216:219], v[100:103]
	v_mfma_f32_16x16x32_bf16 v[92:95], v[156:159], v[216:219], v[92:95]
	v_mfma_f32_16x16x32_bf16 v[84:87], v[148:151], v[232:235], v[84:87]
	v_mfma_f32_16x16x32_bf16 v[76:79], v[156:159], v[232:235], v[76:79]
	v_mfma_f32_16x16x32_bf16 v[112:115], v[164:167], v[180:183], v[112:115]
	v_mfma_f32_16x16x32_bf16 v[104:107], v[172:175], v[180:183], v[104:107]
	v_mfma_f32_16x16x32_bf16 v[96:99], v[164:167], v[188:191], v[96:99]
	v_mfma_f32_16x16x32_bf16 v[88:91], v[172:175], v[188:191], v[88:91]
	v_mfma_f32_16x16x32_bf16 v[80:83], v[164:167], v[212:215], v[80:83]
	v_mfma_f32_16x16x32_bf16 v[72:75], v[172:175], v[212:215], v[72:75]
	v_mfma_f32_16x16x32_bf16 v[68:71], v[164:167], v[220:223], v[68:71]
	v_mfma_f32_16x16x32_bf16 v[64:67], v[172:175], v[220:223], v[64:67]
	v_mfma_f32_16x16x32_bf16 v[112:115], v[168:171], v[184:187], v[112:115]
	v_mfma_f32_16x16x32_bf16 v[104:107], v[176:179], v[184:187], v[104:107]
	v_mfma_f32_16x16x32_bf16 v[96:99], v[168:171], v[192:195], v[96:99]
	v_mfma_f32_16x16x32_bf16 v[88:91], v[176:179], v[192:195], v[88:91]
	v_mfma_f32_16x16x32_bf16 v[80:83], v[168:171], v[216:219], v[80:83]
	v_mfma_f32_16x16x32_bf16 v[72:75], v[176:179], v[216:219], v[72:75]
	v_mfma_f32_16x16x32_bf16 v[68:71], v[168:171], v[232:235], v[68:71]
	v_mfma_f32_16x16x32_bf16 v[64:67], v[176:179], v[232:235], v[64:67]
	s_barrier
	s_add_i32 s41, s41, s20
	v_lshl_add_u64 v[204:205], v[204:205], 0, s[10:11]
	s_mov_b32 m0, s41
	ds_read_b128 v[180:183], v142 offset:49152
	ds_read_b128 v[184:187], v142 offset:50176
	ds_read_b128 v[188:191], v142 offset:51200
	ds_read_b128 v[192:195], v142 offset:52224
	ds_read_b128 v[212:215], v142 offset:53248
	ds_read_b128 v[216:219], v142 offset:54272
	ds_read_b128 v[220:223], v142 offset:55296
	ds_read_b128 v[232:235], v142 offset:56320
	global_load_lds_dwordx4 v[204:205], off
	s_add_i32 m0, s41, 0x2000
	s_add_u32 s50, s50, 0x40080
	v_lshl_add_u64 v[204:205], v[206:207], 0, s[10:11]
	s_addc_u32 s51, s51, 0
	s_add_i32 s41, s47, s20
	global_load_lds_dwordx4 v[204:205], off
	v_lshl_add_u64 v[204:205], s[50:51], 0, v[196:197]
	s_mov_b32 m0, s41
	s_nop 0
	global_load_lds_dwordx4 v[204:205], off
	v_lshl_add_u64 v[204:205], s[50:51], 0, v[128:129]
	s_add_i32 m0, s41, 0x2000
	s_nop 0
	global_load_lds_dwordx4 v[204:205], off
	v_lshl_add_u64 v[204:205], v[236:237], 0, s[10:11]
	s_mov_b32 m0, s26
	s_nop 0
	global_load_lds_dwordx4 v[204:205], off
	v_lshl_add_u64 v[204:205], v[238:239], 0, s[10:11]
	s_mov_b32 m0, s27
	s_nop 0
	global_load_lds_dwordx4 v[204:205], off
	s_waitcnt vmcnt(8)
	s_cmp_eq_u32 s96, 0
	s_cbranch_scc1 .Lgl3
	s_waitcnt lgkmcnt(0)
.Lgl3:
	s_barrier
	s_waitcnt lgkmcnt(0)
	v_mfma_f32_16x16x32_bf16 v[60:63], v[144:147], v[180:183], v[60:63]
	v_mfma_f32_16x16x32_bf16 v[56:59], v[152:155], v[180:183], v[56:59]
	v_mfma_f32_16x16x32_bf16 v[52:55], v[144:147], v[188:191], v[52:55]
	v_mfma_f32_16x16x32_bf16 v[44:47], v[152:155], v[188:191], v[44:47]
	v_mfma_f32_16x16x32_bf16 v[36:39], v[144:147], v[212:215], v[36:39]
	v_mfma_f32_16x16x32_bf16 v[28:31], v[152:155], v[212:215], v[28:31]
	v_mfma_f32_16x16x32_bf16 v[20:23], v[144:147], v[220:223], v[20:23]
	v_mfma_f32_16x16x32_bf16 v[12:15], v[152:155], v[220:223], v[12:15]
	v_mfma_f32_16x16x32_bf16 v[60:63], v[148:151], v[184:187], v[60:63]
	v_mfma_f32_16x16x32_bf16 v[56:59], v[156:159], v[184:187], v[56:59]
	v_mfma_f32_16x16x32_bf16 v[52:55], v[148:151], v[192:195], v[52:55]
	v_mfma_f32_16x16x32_bf16 v[44:47], v[156:159], v[192:195], v[44:47]
	v_mfma_f32_16x16x32_bf16 v[36:39], v[148:151], v[216:219], v[36:39]
	v_mfma_f32_16x16x32_bf16 v[28:31], v[156:159], v[216:219], v[28:31]
	v_mfma_f32_16x16x32_bf16 v[20:23], v[148:151], v[232:235], v[20:23]
	v_mfma_f32_16x16x32_bf16 v[12:15], v[156:159], v[232:235], v[12:15]
	v_mfma_f32_16x16x32_bf16 v[48:51], v[164:167], v[180:183], v[48:51]
	v_mfma_f32_16x16x32_bf16 v[40:43], v[172:175], v[180:183], v[40:43]
	v_mfma_f32_16x16x32_bf16 v[32:35], v[164:167], v[188:191], v[32:35]
	v_mfma_f32_16x16x32_bf16 v[24:27], v[172:175], v[188:191], v[24:27]
	v_mfma_f32_16x16x32_bf16 v[16:19], v[164:167], v[212:215], v[16:19]
	v_mfma_f32_16x16x32_bf16 v[8:11], v[172:175], v[212:215], v[8:11]
	v_mfma_f32_16x16x32_bf16 v[4:7], v[164:167], v[220:223], v[4:7]
	v_mfma_f32_16x16x32_bf16 v[0:3], v[172:175], v[220:223], v[0:3]
	v_mfma_f32_16x16x32_bf16 v[48:51], v[168:171], v[184:187], v[48:51]
	v_mfma_f32_16x16x32_bf16 v[40:43], v[176:179], v[184:187], v[40:43]
	v_mfma_f32_16x16x32_bf16 v[32:35], v[168:171], v[192:195], v[32:35]
	v_mfma_f32_16x16x32_bf16 v[24:27], v[176:179], v[192:195], v[24:27]
	v_mfma_f32_16x16x32_bf16 v[16:19], v[168:171], v[216:219], v[16:19]
	v_mfma_f32_16x16x32_bf16 v[8:11], v[176:179], v[216:219], v[8:11]
	v_mfma_f32_16x16x32_bf16 v[4:7], v[168:171], v[232:235], v[4:7]
	v_mfma_f32_16x16x32_bf16 v[0:3], v[176:179], v[232:235], v[0:3]
	s_barrier
	s_add_i32 s37, s37, 2
	s_add_u32 s48, s48, 0x100
	s_addc_u32 s49, s49, 0
	s_add_u32 s35, s35, 0x100
	s_addc_u32 s36, s36, 0
	s_cmp_gt_u32 s37, 13
	s_cbranch_scc0 .LBB0_98
	s_and_b64 vcc, exec, s[16:17]
	s_cbranch_vccz .LBB0_101
	s_barrier

.LBB0_686:
	s_or_b64 exec, exec, s[6:7]
	v_readfirstlane_b32 s96, v211
	s_lshr_b32 s96, s96, 8
	s_waitcnt lgkmcnt(0)
	v_mov_b32_e32 v0, v211
	s_mov_b32 s3, s74
	s_mov_b32 s13, s94
	v_readlane_b32 s0, v255, 31
	s_mov_b64 s[6:7], s[92:93]
	v_mov_b32_e32 v142, v211
	s_barrier
	s_cmpk_lt_i32 s3, 0x100
	v_readfirstlane_b32 s1, v142
	s_cbranch_scc0 .LBB0_738
	s_ashr_i32 s20, s3, 31
	s_lshr_b32 s2, s20, 29
	s_add_i32 s12, s3, s2
	s_and_b32 s2, s12, -8
	s_sub_i32 s2, s3, s2
	s_cmp_gt_i32 s2, -1
	s_mov_b64 s[8:9], -1
	s_cbranch_scc0 .LBB0_689
	s_lshl_b32 s4, s2, 5
	s_mov_b64 s[8:9], 0

.LBB0_701:
	s_add_u32 s48, s14, s46
	s_addc_u32 s49, s15, s47
	s_add_u32 s48, s48, 0x100
	s_addc_u32 s49, s49, 0
	s_add_u32 s55, s36, s46
	s_addc_u32 s56, s37, s47
	s_add_i32 s57, 0, 0x10000
	s_cmpk_eq_i32 s46, 0x700
	s_cselect_b32 s51, s19, s49
	s_cselect_b32 s50, s52, s48
	v_add_u32_e32 v147, s57, v144
	s_cselect_b32 s49, s17, s56
	s_cselect_b32 s48, s53, s55
	s_add_i32 s55, 0, 0x14000
	ds_read_b128 v[148:151], v147
	ds_read_b128 v[152:155], v147 offset:1024
	ds_read_b128 v[156:159], v147 offset:2048
	ds_read_b128 v[164:167], v147 offset:3072
	v_add_u32_e32 v147, s55, v144
	ds_read_b128 v[168:171], v147
	ds_read_b128 v[172:175], v147 offset:1024
	ds_read_b128 v[176:179], v147 offset:2048
	ds_read_b128 v[180:183], v147 offset:3072
	v_lshl_add_u64 v[236:237], v[138:139], 0, s[46:47]
	s_add_i32 m0, s9, 0xc000
	ds_read_b128 v[184:187], v145
	ds_read_b128 v[188:191], v145 offset:1024
	ds_read_b128 v[192:195], v145 offset:2048
	ds_read_b128 v[204:207], v145 offset:3072
	ds_read_b128 v[212:215], v145 offset:4096
	ds_read_b128 v[216:219], v145 offset:5120
	ds_read_b128 v[220:223], v145 offset:6144
	ds_read_b128 v[232:235], v145 offset:7168
	global_load_lds_dwordx4 v[236:237], off
	v_lshl_add_u64 v[236:237], v[140:141], 0, s[46:47]
	s_add_i32 m0, s9, 0xe000
	s_nop 0
	global_load_lds_dwordx4 v[236:237], off
	s_waitcnt vmcnt(8)
	s_cmp_eq_u32 s96, 0
	s_cbranch_scc1 .Lgl4
	s_waitcnt lgkmcnt(0)
.Lgl4:
	s_barrier
	s_waitcnt lgkmcnt(0)
	v_mfma_f32_16x16x32_bf16 v[68:71], v[148:151], v[184:187], v[68:71]
	v_mfma_f32_16x16x32_bf16 v[64:67], v[156:159], v[184:187], v[64:67]
	v_mfma_f32_16x16x32_bf16 v[112:115], v[148:151], v[192:195], v[112:115]
	v_mfma_f32_16x16x32_bf16 v[108:111], v[156:159], v[192:195], v[108:111]
	v_mfma_f32_16x16x32_bf16 v[76:79], v[148:151], v[212:215], v[76:79]
	v_mfma_f32_16x16x32_bf16 v[72:75], v[156:159], v[212:215], v[72:75]
	v_mfma_f32_16x16x32_bf16 v[92:95], v[148:151], v[220:223], v[92:95]
	v_mfma_f32_16x16x32_bf16 v[88:91], v[156:159], v[220:223], v[88:91]
	v_mfma_f32_16x16x32_bf16 v[68:71], v[152:155], v[188:191], v[68:71]
	v_mfma_f32_16x16x32_bf16 v[64:67], v[164:167], v[188:191], v[64:67]
	v_mfma_f32_16x16x32_bf16 v[112:115], v[152:155], v[204:207], v[112:115]
	v_mfma_f32_16x16x32_bf16 v[108:111], v[164:167], v[204:207], v[108:111]
	v_mfma_f32_16x16x32_bf16 v[76:79], v[152:155], v[216:219], v[76:79]
	v_mfma_f32_16x16x32_bf16 v[72:75], v[164:167], v[216:219], v[72:75]
	v_mfma_f32_16x16x32_bf16 v[92:95], v[152:155], v[232:235], v[92:95]
	v_mfma_f32_16x16x32_bf16 v[88:91], v[164:167], v[232:235], v[88:91]
	v_mfma_f32_16x16x32_bf16 v[96:99], v[168:171], v[184:187], v[96:99]
	v_mfma_f32_16x16x32_bf16 v[100:103], v[176:179], v[184:187], v[100:103]
	v_mfma_f32_16x16x32_bf16 v[120:123], v[168:171], v[192:195], v[120:123]
	v_mfma_f32_16x16x32_bf16 v[124:127], v[176:179], v[192:195], v[124:127]
	v_mfma_f32_16x16x32_bf16 v[84:87], v[168:171], v[212:215], v[84:87]
	v_mfma_f32_16x16x32_bf16 v[80:83], v[176:179], v[212:215], v[80:83]
	v_mfma_f32_16x16x32_bf16 v[116:119], v[168:171], v[220:223], v[116:119]
	v_mfma_f32_16x16x32_bf16 v[104:107], v[176:179], v[220:223], v[104:107]
	v_mfma_f32_16x16x32_bf16 v[96:99], v[172:175], v[188:191], v[96:99]
	v_mfma_f32_16x16x32_bf16 v[100:103], v[180:183], v[188:191], v[100:103]
	v_mfma_f32_16x16x32_bf16 v[120:123], v[172:175], v[204:207], v[120:123]
	v_mfma_f32_16x16x32_bf16 v[124:127], v[180:183], v[204:207], v[124:127]
	v_mfma_f32_16x16x32_bf16 v[84:87], v[172:175], v[216:219], v[84:87]
	v_mfma_f32_16x16x32_bf16 v[80:83], v[180:183], v[216:219], v[80:83]
	v_mfma_f32_16x16x32_bf16 v[116:119], v[172:175], v[232:235], v[116:119]
	v_mfma_f32_16x16x32_bf16 v[104:107], v[180:183], v[232:235], v[104:107]
	s_barrier
	s_add_i32 s56, s57, s25
	v_lshl_add_u64 v[236:237], s[48:49], 0, v[196:197]
	s_mov_b32 m0, s56
	ds_read_b128 v[184:187], v145 offset:16384
	ds_read_b128 v[188:191], v145 offset:17408
	ds_read_b128 v[192:195], v145 offset:18432
	ds_read_b128 v[204:207], v145 offset:19456
	ds_read_b128 v[212:215], v145 offset:20480
	ds_read_b128 v[216:219], v145 offset:21504
	ds_read_b128 v[220:223], v145 offset:22528
	ds_read_b128 v[232:235], v145 offset:23552
	global_load_lds_dwordx4 v[236:237], off
	s_add_i32 m0, s56, 0x2000
	s_add_u32 s56, s48, 0x40000
	v_lshl_add_u64 v[238:239], s[48:49], 0, v[132:133]
	s_addc_u32 s57, s49, 0
	s_add_i32 s55, s55, s25
	global_load_lds_dwordx4 v[238:239], off
	v_lshl_add_u64 v[240:241], s[56:57], 0, v[196:197]
	s_mov_b32 m0, s55
	v_lshl_add_u64 v[242:243], s[50:51], 0, v[130:131]
	global_load_lds_dwordx4 v[240:241], off
	v_lshl_add_u64 v[240:241], s[56:57], 0, v[132:133]
	s_add_i32 m0, s55, 0x2000
	s_nop 0
	global_load_lds_dwordx4 v[240:241], off
	v_lshl_add_u64 v[240:241], s[50:51], 0, v[128:129]
	s_mov_b32 m0, s9
	s_nop 0
	global_load_lds_dwordx4 v[240:241], off
	s_mov_b32 m0, s27
	s_nop 0
	global_load_lds_dwordx4 v[242:243], off
	s_waitcnt vmcnt(8)
	s_cmp_eq_u32 s96, 0
	s_cbranch_scc1 .Lgl5
	s_waitcnt lgkmcnt(0)
.Lgl5:
	s_barrier
	s_waitcnt lgkmcnt(0)
	v_mfma_f32_16x16x32_bf16 v[60:63], v[148:151], v[184:187], v[60:63]
	v_mfma_f32_16x16x32_bf16 v[56:59], v[156:159], v[184:187], v[56:59]
	v_mfma_f32_16x16x32_bf16 v[44:47], v[148:151], v[192:195], v[44:47]
	v_mfma_f32_16x16x32_bf16 v[40:43], v[156:159], v[192:195], v[40:43]
	v_mfma_f32_16x16x32_bf16 v[28:31], v[148:151], v[212:215], v[28:31]
	v_mfma_f32_16x16x32_bf16 v[24:27], v[156:159], v[212:215], v[24:27]
	v_mfma_f32_16x16x32_bf16 v[12:15], v[148:151], v[220:223], v[12:15]
	v_mfma_f32_16x16x32_bf16 v[8:11], v[156:159], v[220:223], v[8:11]
	v_mfma_f32_16x16x32_bf16 v[60:63], v[152:155], v[188:191], v[60:63]
	v_mfma_f32_16x16x32_bf16 v[56:59], v[164:167], v[188:191], v[56:59]
	v_mfma_f32_16x16x32_bf16 v[44:47], v[152:155], v[204:207], v[44:47]
	v_mfma_f32_16x16x32_bf16 v[40:43], v[164:167], v[204:207], v[40:43]
	v_mfma_f32_16x16x32_bf16 v[28:31], v[152:155], v[216:219], v[28:31]
	v_mfma_f32_16x16x32_bf16 v[24:27], v[164:167], v[216:219], v[24:27]
	v_mfma_f32_16x16x32_bf16 v[12:15], v[152:155], v[232:235], v[12:15]
	v_mfma_f32_16x16x32_bf16 v[8:11], v[164:167], v[232:235], v[8:11]
	v_mfma_f32_16x16x32_bf16 v[52:55], v[168:171], v[184:187], v[52:55]
	v_mfma_f32_16x16x32_bf16 v[48:51], v[176:179], v[184:187], v[48:51]
	v_mfma_f32_16x16x32_bf16 v[36:39], v[168:171], v[192:195], v[36:39]
	v_mfma_f32_16x16x32_bf16 v[32:35], v[176:179], v[192:195], v[32:35]
	v_mfma_f32_16x16x32_bf16 v[20:23], v[168:171], v[212:215], v[20:23]
	v_mfma_f32_16x16x32_bf16 v[16:19], v[176:179], v[212:215], v[16:19]
	v_mfma_f32_16x16x32_bf16 v[4:7], v[168:171], v[220:223], v[4:7]
	v_mfma_f32_16x16x32_bf16 v[0:3], v[176:179], v[220:223], v[0:3]
	v_mfma_f32_16x16x32_bf16 v[52:55], v[172:175], v[188:191], v[52:55]
	v_mfma_f32_16x16x32_bf16 v[48:51], v[180:183], v[188:191], v[48:51]
	v_mfma_f32_16x16x32_bf16 v[36:39], v[172:175], v[204:207], v[36:39]
	v_mfma_f32_16x16x32_bf16 v[32:35], v[180:183], v[204:207], v[32:35]
	v_mfma_f32_16x16x32_bf16 v[20:23], v[172:175], v[216:219], v[20:23]
	v_mfma_f32_16x16x32_bf16 v[16:19], v[180:183], v[216:219], v[16:19]
	v_mfma_f32_16x16x32_bf16 v[4:7], v[172:175], v[232:235], v[4:7]
	v_mfma_f32_16x16x32_bf16 v[0:3], v[180:183], v[232:235], v[0:3]
	s_barrier
	s_add_i32 s55, 0, 0x18000
	v_add_u32_e32 v147, s55, v144
	s_add_i32 s56, 0, 0x1c000
	ds_read_b128 v[148:151], v147
	ds_read_b128 v[152:155], v147 offset:1024
	ds_read_b128 v[156:159], v147 offset:2048
	ds_read_b128 v[164:167], v147 offset:3072
	v_add_u32_e32 v147, s56, v144
	ds_read_b128 v[168:171], v147
	ds_read_b128 v[172:175], v147 offset:1024
	ds_read_b128 v[176:179], v147 offset:2048
	ds_read_b128 v[180:183], v147 offset:3072
	s_add_u32 s50, s50, 0x40000
	s_addc_u32 s51, s51, 0
	s_mov_b32 m0, s28
	v_lshl_add_u64 v[244:245], s[50:51], 0, v[128:129]
	ds_read_b128 v[184:187], v145 offset:32768
	ds_read_b128 v[188:191], v145 offset:33792
	ds_read_b128 v[192:195], v145 offset:34816
	ds_read_b128 v[204:207], v145 offset:35840
	ds_read_b128 v[212:215], v145 offset:36864
	ds_read_b128 v[216:219], v145 offset:37888
	ds_read_b128 v[220:223], v145 offset:38912
	ds_read_b128 v[232:235], v145 offset:39936
	global_load_lds_dwordx4 v[244:245], off
	v_lshl_add_u64 v[244:245], s[50:51], 0, v[130:131]
	s_mov_b32 m0, s29
	s_nop 0
	global_load_lds_dwordx4 v[244:245], off
	s_waitcnt vmcnt(8)
	s_cmp_eq_u32 s96, 0
	s_cbranch_scc1 .Lgl6
	s_waitcnt lgkmcnt(0)
.Lgl6:
	s_barrier
	s_waitcnt lgkmcnt(0)
	v_mfma_f32_16x16x32_bf16 v[68:71], v[148:151], v[184:187], v[68:71]
	v_mfma_f32_16x16x32_bf16 v[64:67], v[156:159], v[184:187], v[64:67]
	v_mfma_f32_16x16x32_bf16 v[112:115], v[148:151], v[192:195], v[112:115]
	v_mfma_f32_16x16x32_bf16 v[108:111], v[156:159], v[192:195], v[108:111]
	v_mfma_f32_16x16x32_bf16 v[76:79], v[148:151], v[212:215], v[76:79]
	v_mfma_f32_16x16x32_bf16 v[72:75], v[156:159], v[212:215], v[72:75]
	v_mfma_f32_16x16x32_bf16 v[92:95], v[148:151], v[220:223], v[92:95]
	v_mfma_f32_16x16x32_bf16 v[88:91], v[156:159], v[220:223], v[88:91]
	v_mfma_f32_16x16x32_bf16 v[68:71], v[152:155], v[188:191], v[68:71]
	v_mfma_f32_16x16x32_bf16 v[64:67], v[164:167], v[188:191], v[64:67]
	v_mfma_f32_16x16x32_bf16 v[112:115], v[152:155], v[204:207], v[112:115]
	v_mfma_f32_16x16x32_bf16 v[108:111], v[164:167], v[204:207], v[108:111]
	v_mfma_f32_16x16x32_bf16 v[76:79], v[152:155], v[216:219], v[76:79]
	v_mfma_f32_16x16x32_bf16 v[72:75], v[164:167], v[216:219], v[72:75]
	v_mfma_f32_16x16x32_bf16 v[92:95], v[152:155], v[232:235], v[92:95]
	v_mfma_f32_16x16x32_bf16 v[88:91], v[164:167], v[232:235], v[88:91]
	v_mfma_f32_16x16x32_bf16 v[96:99], v[168:171], v[184:187], v[96:99]
	v_mfma_f32_16x16x32_bf16 v[100:103], v[176:179], v[184:187], v[100:103]
	v_mfma_f32_16x16x32_bf16 v[120:123], v[168:171], v[192:195], v[120:123]
	v_mfma_f32_16x16x32_bf16 v[124:127], v[176:179], v[192:195], v[124:127]
	v_mfma_f32_16x16x32_bf16 v[84:87], v[168:171], v[212:215], v[84:87]
	v_mfma_f32_16x16x32_bf16 v[80:83], v[176:179], v[212:215], v[80:83]
	v_mfma_f32_16x16x32_bf16 v[116:119], v[168:171], v[220:223], v[116:119]
	v_mfma_f32_16x16x32_bf16 v[104:107], v[176:179], v[220:223], v[104:107]
	v_mfma_f32_16x16x32_bf16 v[96:99], v[172:175], v[188:191], v[96:99]
	v_mfma_f32_16x16x32_bf16 v[100:103], v[180:183], v[188:191], v[100:103]
	v_mfma_f32_16x16x32_bf16 v[120:123], v[172:175], v[204:207], v[120:123]
	v_mfma_f32_16x16x32_bf16 v[124:127], v[180:183], v[204:207], v[124:127]
	v_mfma_f32_16x16x32_bf16 v[84:87], v[172:175], v[216:219], v[84:87]
	v_mfma_f32_16x16x32_bf16 v[80:83], v[180:183], v[216:219], v[80:83]
	v_mfma_f32_16x16x32_bf16 v[116:119], v[172:175], v[232:235], v[116:119]
	v_mfma_f32_16x16x32_bf16 v[104:107], v[180:183], v[232:235], v[104:107]
	s_barrier
	s_add_i32 s50, s55, s25
	v_lshl_add_u64 v[236:237], v[236:237], 0, s[10:11]
	s_mov_b32 m0, s50
	ds_read_b128 v[184:187], v145 offset:49152
	ds_read_b128 v[188:191], v145 offset:50176
	ds_read_b128 v[192:195], v145 offset:51200
	ds_read_b128 v[204:207], v145 offset:52224
	ds_read_b128 v[212:215], v145 offset:53248
	ds_read_b128 v[216:219], v145 offset:54272
	ds_read_b128 v[220:223], v145 offset:55296
	ds_read_b128 v[232:235], v145 offset:56320
	global_load_lds_dwordx4 v[236:237], off
	s_add_i32 m0, s50, 0x2000
	s_add_u32 s48, s48, 0x40080
	v_lshl_add_u64 v[236:237], v[238:239], 0, s[10:11]
	s_addc_u32 s49, s49, 0
	s_add_i32 s50, s56, s25
	global_load_lds_dwordx4 v[236:237], off
	v_lshl_add_u64 v[236:237], s[48:49], 0, v[196:197]
	s_mov_b32 m0, s50
	s_nop 0
	global_load_lds_dwordx4 v[236:237], off
	v_lshl_add_u64 v[236:237], s[48:49], 0, v[132:133]
	s_add_i32 m0, s50, 0x2000
	s_nop 0
	global_load_lds_dwordx4 v[236:237], off
	v_lshl_add_u64 v[236:237], v[240:241], 0, s[10:11]
	s_mov_b32 m0, s4
	s_nop 0
	global_load_lds_dwordx4 v[236:237], off
	v_lshl_add_u64 v[236:237], v[242:243], 0, s[10:11]
	s_mov_b32 m0, s31
	s_nop 0
	global_load_lds_dwordx4 v[236:237], off
	s_waitcnt vmcnt(8)
	s_cmp_eq_u32 s96, 0
	s_cbranch_scc1 .Lgl7
	s_waitcnt lgkmcnt(0)
.Lgl7:
	s_barrier
	s_waitcnt lgkmcnt(0)
	v_mfma_f32_16x16x32_bf16 v[60:63], v[148:151], v[184:187], v[60:63]
	v_mfma_f32_16x16x32_bf16 v[56:59], v[156:159], v[184:187], v[56:59]
	v_mfma_f32_16x16x32_bf16 v[44:47], v[148:151], v[192:195], v[44:47]
	v_mfma_f32_16x16x32_bf16 v[40:43], v[156:159], v[192:195], v[40:43]
	v_mfma_f32_16x16x32_bf16 v[28:31], v[148:151], v[212:215], v[28:31]
	v_mfma_f32_16x16x32_bf16 v[24:27], v[156:159], v[212:215], v[24:27]
	v_mfma_f32_16x16x32_bf16 v[12:15], v[148:151], v[220:223], v[12:15]
	v_mfma_f32_16x16x32_bf16 v[8:11], v[156:159], v[220:223], v[8:11]
	v_mfma_f32_16x16x32_bf16 v[60:63], v[152:155], v[188:191], v[60:63]
	v_mfma_f32_16x16x32_bf16 v[56:59], v[164:167], v[188:191], v[56:59]
	v_mfma_f32_16x16x32_bf16 v[44:47], v[152:155], v[204:207], v[44:47]
	v_mfma_f32_16x16x32_bf16 v[40:43], v[164:167], v[204:207], v[40:43]
	v_mfma_f32_16x16x32_bf16 v[28:31], v[152:155], v[216:219], v[28:31]
	v_mfma_f32_16x16x32_bf16 v[24:27], v[164:167], v[216:219], v[24:27]
	v_mfma_f32_16x16x32_bf16 v[12:15], v[152:155], v[232:235], v[12:15]
	v_mfma_f32_16x16x32_bf16 v[8:11], v[164:167], v[232:235], v[8:11]
	v_mfma_f32_16x16x32_bf16 v[52:55], v[168:171], v[184:187], v[52:55]
	v_mfma_f32_16x16x32_bf16 v[48:51], v[176:179], v[184:187], v[48:51]
	v_mfma_f32_16x16x32_bf16 v[36:39], v[168:171], v[192:195], v[36:39]
	v_mfma_f32_16x16x32_bf16 v[32:35], v[176:179], v[192:195], v[32:35]
	v_mfma_f32_16x16x32_bf16 v[20:23], v[168:171], v[212:215], v[20:23]
	v_mfma_f32_16x16x32_bf16 v[16:19], v[176:179], v[212:215], v[16:19]
	v_mfma_f32_16x16x32_bf16 v[4:7], v[168:171], v[220:223], v[4:7]
	v_mfma_f32_16x16x32_bf16 v[0:3], v[176:179], v[220:223], v[0:3]
	v_mfma_f32_16x16x32_bf16 v[52:55], v[172:175], v[188:191], v[52:55]
	v_mfma_f32_16x16x32_bf16 v[48:51], v[180:183], v[188:191], v[48:51]
	v_mfma_f32_16x16x32_bf16 v[36:39], v[172:175], v[204:207], v[36:39]
	v_mfma_f32_16x16x32_bf16 v[32:35], v[180:183], v[204:207], v[32:35]
	v_mfma_f32_16x16x32_bf16 v[20:23], v[172:175], v[216:219], v[20:23]
	v_mfma_f32_16x16x32_bf16 v[16:19], v[180:183], v[216:219], v[16:19]
	v_mfma_f32_16x16x32_bf16 v[4:7], v[172:175], v[232:235], v[4:7]
	v_mfma_f32_16x16x32_bf16 v[0:3], v[180:183], v[232:235], v[0:3]
	s_barrier
	s_add_i32 s54, s54, 2
	s_add_u32 s46, s46, 0x100
	s_addc_u32 s47, s47, 0
	s_cmp_gt_u32 s54, 13
	s_cbranch_scc0 .LBB0_701
	s_add_u32 s46, s36, 0xffffff00
	s_addc_u32 s47, s37, -1
	s_andn2_b64 vcc, exec, s[40:41]
	s_cbranch_vccnz .LBB0_704
	v_mov_b32_e32 v0, 0
	s_mov_b32 s12, s16
	s_mov_b32 s8, s18
	s_mov_b64 s[14:15], s[44:45]
	s_mov_b32 s34, s35
	v_mov_b32_e32 v1, v0
	v_mov_b32_e32 v2, v0
	v_mov_b32_e32 v3, v0
	v_mov_b32_e32 v4, v0
	v_mov_b32_e32 v5, v0
	v_mov_b32_e32 v6, v0
	v_mov_b32_e32 v7, v0
	v_mov_b32_e32 v16, v0
	v_mov_b32_e32 v17, v0
	v_mov_b32_e32 v18, v0
	v_mov_b32_e32 v19, v0
	v_mov_b32_e32 v20, v0
	v_mov_b32_e32 v21, v0
	v_mov_b32_e32 v22, v0
	v_mov_b32_e32 v23, v0
	v_mov_b32_e32 v32, v0
	v_mov_b32_e32 v33, v0
	v_mov_b32_e32 v34, v0
	v_mov_b32_e32 v35, v0
	v_mov_b32_e32 v36, v0
	v_mov_b32_e32 v37, v0
	v_mov_b32_e32 v38, v0
	v_mov_b32_e32 v39, v0
	v_mov_b32_e32 v48, v0
	v_mov_b32_e32 v49, v0
	v_mov_b32_e32 v50, v0
	v_mov_b32_e32 v51, v0
	v_mov_b32_e32 v52, v0
	v_mov_b32_e32 v53, v0
	v_mov_b32_e32 v54, v0
	v_mov_b32_e32 v55, v0
	v_mov_b32_e32 v8, v0
	v_mov_b32_e32 v9, v0
	v_mov_b32_e32 v10, v0
	v_mov_b32_e32 v11, v0
	v_mov_b32_e32 v12, v0
	v_mov_b32_e32 v13, v0
	v_mov_b32_e32 v14, v0
	v_mov_b32_e32 v15, v0
	v_mov_b32_e32 v24, v0
	v_mov_b32_e32 v25, v0
	v_mov_b32_e32 v26, v0
	v_mov_b32_e32 v27, v0
	v_mov_b32_e32 v28, v0
	v_mov_b32_e32 v29, v0
	v_mov_b32_e32 v30, v0
	v_mov_b32_e32 v31, v0
	v_mov_b32_e32 v40, v0
	v_mov_b32_e32 v41, v0
	v_mov_b32_e32 v42, v0
	v_mov_b32_e32 v43, v0
	v_mov_b32_e32 v44, v0
	v_mov_b32_e32 v45, v0
	v_mov_b32_e32 v46, v0
	v_mov_b32_e32 v47, v0
	v_mov_b32_e32 v56, v0
	v_mov_b32_e32 v57, v0
	v_mov_b32_e32 v58, v0
	v_mov_b32_e32 v59, v0
	v_mov_b32_e32 v60, v0
	v_mov_b32_e32 v61, v0
	v_mov_b32_e32 v62, v0
	v_mov_b32_e32 v63, v0
	v_mov_b32_e32 v104, v0
	v_mov_b32_e32 v105, v0
	v_mov_b32_e32 v106, v0
	v_mov_b32_e32 v107, v0
	v_mov_b32_e32 v116, v0
	v_mov_b32_e32 v117, v0
	v_mov_b32_e32 v118, v0
	v_mov_b32_e32 v119, v0
	v_mov_b32_e32 v80, v0
	v_mov_b32_e32 v81, v0
	v_mov_b32_e32 v82, v0
	v_mov_b32_e32 v83, v0
	v_mov_b32_e32 v84, v0
	v_mov_b32_e32 v85, v0
	v_mov_b32_e32 v86, v0
	v_mov_b32_e32 v87, v0
	v_mov_b32_e32 v124, v0
	v_mov_b32_e32 v125, v0
	v_mov_b32_e32 v126, v0
	v_mov_b32_e32 v127, v0
	v_mov_b32_e32 v120, v0
	v_mov_b32_e32 v121, v0
	v_mov_b32_e32 v122, v0
	v_mov_b32_e32 v123, v0
	v_mov_b32_e32 v100, v0
	v_mov_b32_e32 v101, v0
	v_mov_b32_e32 v102, v0
	v_mov_b32_e32 v103, v0
	v_mov_b32_e32 v96, v0
	v_mov_b32_e32 v97, v0
	v_mov_b32_e32 v98, v0
	v_mov_b32_e32 v99, v0
	v_mov_b32_e32 v88, v0
	v_mov_b32_e32 v89, v0
	v_mov_b32_e32 v90, v0
	v_mov_b32_e32 v91, v0
	v_mov_b32_e32 v92, v0
	v_mov_b32_e32 v93, v0
	v_mov_b32_e32 v94, v0
	v_mov_b32_e32 v95, v0
	v_mov_b32_e32 v72, v0
	v_mov_b32_e32 v73, v0
	v_mov_b32_e32 v74, v0
	v_mov_b32_e32 v75, v0
	v_mov_b32_e32 v76, v0
	v_mov_b32_e32 v77, v0
	v_mov_b32_e32 v78, v0
	v_mov_b32_e32 v79, v0
	v_mov_b32_e32 v108, v0
	v_mov_b32_e32 v109, v0
	v_mov_b32_e32 v110, v0
	v_mov_b32_e32 v111, v0
	v_mov_b32_e32 v112, v0
	v_mov_b32_e32 v113, v0
	v_mov_b32_e32 v114, v0
	v_mov_b32_e32 v115, v0
	v_mov_b32_e32 v64, v0
	v_mov_b32_e32 v65, v0
	v_mov_b32_e32 v66, v0
	v_mov_b32_e32 v67, v0
	v_mov_b32_e32 v68, v0
	v_mov_b32_e32 v69, v0
	v_mov_b32_e32 v70, v0
	v_mov_b32_e32 v71, v0
	s_movk_i32 s52, 0x1fff
	s_mov_b32 s53, 0x7ffff
	s_andn2_b64 vcc, exec, s[38:39]
	s_cbranch_vccnz .LBB0_705
	s_branch .LBB0_706

.LBB0_790:
	s_or_b64 exec, exec, s[6:7]
	v_readfirstlane_b32 s96, v211
	s_lshr_b32 s96, s96, 8
	s_waitcnt lgkmcnt(0)
	v_mov_b32_e32 v0, v211
	s_mov_b32 s0, s94
	s_mov_b32 s1, s74
	v_readlane_b32 s2, v255, 31
	s_mov_b64 s[6:7], s[92:93]
	v_mov_b32_e32 v14, v211
	s_barrier
	s_cmpk_gt_i32 s1, 0x57f
	v_readfirstlane_b32 s14, v14
	s_cbranch_scc1 .LBB0_806
	v_lshlrev_b32_e32 v0, 4, v14
	v_add_u32_e32 v1, 0x2000, v0
	v_ashrrev_i32_e32 v2, 31, v1
	v_lshrrev_b32_e32 v2, 22, v2
	v_add_u32_e32 v2, v1, v2
	v_ashrrev_i32_e32 v8, 10, v2
	v_mul_i32_i24_e32 v2, 0x400, v8
	v_sub_u32_e32 v1, v1, v2
	v_lshrrev_b32_e32 v2, 4, v1
	v_bitop3_b32 v1, v2, v1, 32 bitop3:0x6c
	v_ashrrev_i32_e32 v2, 31, v1
	v_lshrrev_b32_e32 v2, 26, v2
	v_add_u32_e32 v2, v1, v2
	v_lshlrev_b32_e32 v3, 3, v8
	v_ashrrev_i32_e32 v9, 6, v2
	v_and_b32_e32 v3, -16, v3
	v_add_u32_e32 v3, v9, v3
	v_and_b32_e32 v4, 3, v9
	s_mov_b32 s4, 0x1fffe0
	v_lshrrev_b32_e32 v5, 2, v3
	v_lshlrev_b32_e32 v6, 1, v3
	v_and_b32_e32 v2, 0xc0, v2
	v_and_or_b32 v4, v3, s4, v4
	v_and_b32_e32 v5, 4, v5
	v_and_b32_e32 v6, 24, v6
	v_sub_u32_e32 v1, v1, v2
	v_or3_b32 v4, v4, v5, v6
	v_lshlrev_b32_e32 v5, 5, v8
	v_ashrrev_i16_sdwa v1, v225, sext(v1) dst_sel:DWORD dst_unused:UNUSED_PAD src0_sel:DWORD src1_sel:BYTE_0
	v_and_b32_e32 v5, 32, v5
	v_bfe_i32 v10, v1, 0, 16
	v_add_lshl_u32 v1, v5, v10, 1
	v_lshl_add_u32 v128, v4, 11, v1
	v_lshl_add_u32 v130, v3, 11, v1
	v_bfe_i32 v1, v14, 27, 1
	v_lshrrev_b32_e32 v1, 22, v1
	v_add_u32_e32 v1, v0, v1
	v_and_b32_e32 v1, 0xfffffc00, v1
	v_sub_u32_e32 v0, v0, v1
	v_lshrrev_b32_e32 v1, 4, v0
	v_ashrrev_i32_e32 v2, 31, v14
	v_bitop3_b32 v0, v1, v0, 32 bitop3:0x6c
	v_lshrrev_b32_e32 v2, 26, v2
	v_ashrrev_i32_e32 v1, 31, v0
	v_add_u32_e32 v2, v14, v2
	s_add_u32 s2, s6, 0xae00000
	v_lshrrev_b32_e32 v1, 26, v1
	v_ashrrev_i32_e32 v12, 6, v2
	s_addc_u32 s3, s7, 0
	v_add_u32_e32 v1, v0, v1
	v_lshlrev_b32_e32 v2, 3, v12
	s_add_u32 s20, s6, 0xa10000
	v_ashrrev_i32_e32 v11, 6, v1
	v_and_b32_e32 v2, -16, v2
	s_addc_u32 s21, s7, 0
	v_add_u32_e32 v2, v11, v2
	v_and_b32_e32 v3, 3, v11
	s_ashr_i32 s23, s1, 31
	v_and_or_b32 v3, v2, s4, v3
	s_lshr_b32 s4, s23, 29
	s_add_i32 s4, s1, s4
	s_ashr_i32 s15, s14, 6
	s_ashr_i32 s8, s4, 3
	s_and_b32 s4, s4, -8
	s_ashr_i32 s16, s14, 8
	s_lshl_b32 s22, s15, 10
	s_sub_i32 s4, s1, s4
	s_cmp_lt_i32 s4, 0
	s_movk_i32 s9, 0xb1
	s_cselect_b32 s9, s9, 0xb0
	s_mul_i32 s4, s4, s9
	s_add_i32 s4, s4, s8
	s_mul_hi_i32 s8, s4, 0x2e8ba2e9
	s_lshr_b32 s9, s8, 31
	s_ashr_i32 s8, s8, 5
	s_add_i32 s8, s8, s9
	s_lshl_b32 s9, s8, 3
	s_mulk_i32 s8, 0xb0
	s_sub_i32 s8, s4, s8
	s_bfe_u32 s4, s8, 0x3001c
	s_add_i32 s12, s8, s4
	s_sext_i32_i16 s4, s12
	s_and_b32 s12, s12, 0xfff8
	s_sub_i32 s8, s8, s12
	s_sext_i32_i16 s8, s8
	v_lshrrev_b32_e32 v4, 2, v2
	v_lshlrev_b32_e32 v5, 1, v2
	v_and_b32_e32 v1, 0xc0, v1
	s_lshr_b32 s4, s4, 3
	s_add_i32 s44, s9, s8
	v_and_b32_e32 v4, 4, v4
	v_and_b32_e32 v5, 24, v5
	v_sub_u32_e32 v0, v0, v1
	s_ashr_i32 s45, s44, 31
	s_bfe_i64 s[12:13], s[4:5], 0x100000
	v_or3_b32 v3, v3, v4, v5
	v_lshlrev_b32_e32 v4, 5, v12
	v_ashrrev_i16_sdwa v0, v225, sext(v0) dst_sel:DWORD dst_unused:UNUSED_PAD src0_sel:DWORD src1_sel:BYTE_0
	s_lshl_b64 s[8:9], s[44:45], 19
	s_lshl_b64 s[12:13], s[12:13], 19
	v_and_b32_e32 v4, 32, v4
	v_bfe_i32 v13, v0, 0, 16
	s_add_u32 s48, s20, s12
	v_add_lshl_u32 v0, v4, v13, 1
	s_addc_u32 s49, s21, s13
	s_add_i32 s24, s22, 0
	v_lshl_add_u32 v196, v3, 11, v0
	s_add_i32 m0, s24, 0x10000
	v_lshl_add_u32 v132, v2, 11, v0
	global_load_lds_dwordx4 v196, s[48:49]
	s_add_i32 m0, s24, 0x12000
	s_add_u32 s12, s48, 0x40000
	global_load_lds_dwordx4 v128, s[48:49]
	s_addc_u32 s13, s49, 0
	s_add_i32 m0, s24, 0x14000
	v_mov_b32_e32 v129, v197
	global_load_lds_dwordx4 v196, s[12:13]
	s_add_i32 m0, s24, 0x16000
	s_add_u32 s46, s2, s8
	s_addc_u32 s47, s3, s9
	s_add_i32 s25, s24, 0x2000
	global_load_lds_dwordx4 v128, s[12:13]
	s_mov_b32 m0, s24
	s_add_u32 s8, s46, 0x40000
	global_load_lds_dwordx4 v132, s[46:47]
	s_mov_b32 m0, s25
	s_addc_u32 s9, s47, 0
	s_add_i32 s26, s24, 0x4000
	global_load_lds_dwordx4 v130, s[46:47]
	s_mov_b32 m0, s26
	s_add_i32 s27, s24, 0x6000
	global_load_lds_dwordx4 v132, s[8:9]
	s_mov_b32 m0, s27
	v_mov_b32_e32 v133, v197
	global_load_lds_dwordx4 v130, s[8:9]
	v_mov_b32_e32 v131, v197
	s_cmp_eq_u32 s16, 1
	v_lshl_add_u64 v[6:7], s[48:49], 0, v[196:197]
	v_lshl_add_u64 v[4:5], s[48:49], 0, v[128:129]
	v_lshl_add_u64 v[0:1], s[46:47], 0, v[132:133]
	s_cselect_b64 s[8:9], -1, 0
	s_cmp_lg_u32 s16, 1
	v_lshl_add_u64 v[2:3], s[46:47], 0, v[130:131]
	s_cbranch_scc1 .LBB0_793
	s_barrier

.LBB0_799:
	s_add_u32 s48, s46, 0xfffc0080
	s_addc_u32 s49, s47, -1
	s_add_i32 s52, 0, 0x10000
	s_cmp_eq_u32 s45, 12
	s_cselect_b32 s51, s19, s49
	s_cselect_b32 s50, s34, s48
	s_cselect_b32 s49, s17, s37
	s_cselect_b32 s48, s35, s36
	s_add_i32 s54, 0, 0x14000
	v_add_u32_e32 v154, s52, v139
	v_add_u32_e32 v158, s54, v139
	ds_read_b128 v[142:145], v154
	ds_read_b128 v[146:149], v154 offset:1024
	ds_read_b128 v[150:153], v154 offset:2048
	ds_read_b128 v[154:157], v154 offset:3072
	ds_read_b128 v[164:167], v158
	ds_read_b128 v[168:171], v158 offset:1024
	ds_read_b128 v[172:175], v158 offset:2048
	ds_read_b128 v[176:179], v158 offset:3072
	v_lshl_add_u64 v[158:159], s[46:47], 0, v[134:135]
	s_add_i32 m0, s24, 0xc000
	ds_read_b128 v[180:183], v141
	ds_read_b128 v[184:187], v141 offset:1024
	ds_read_b128 v[188:191], v141 offset:2048
	ds_read_b128 v[192:195], v141 offset:3072
	ds_read_b128 v[204:207], v141 offset:4096
	ds_read_b128 v[212:215], v141 offset:5120
	ds_read_b128 v[216:219], v141 offset:6144
	ds_read_b128 v[220:223], v141 offset:7168
	global_load_lds_dwordx4 v[158:159], off
	v_lshl_add_u64 v[158:159], s[46:47], 0, v[136:137]
	s_add_i32 m0, s24, 0xe000
	s_nop 0
	global_load_lds_dwordx4 v[158:159], off
	s_waitcnt vmcnt(8)
	s_cmp_eq_u32 s96, 0
	s_cbranch_scc1 .Lgl8
	s_waitcnt lgkmcnt(0)
.Lgl8:
	s_barrier
	s_waitcnt lgkmcnt(0)
	v_mfma_f32_16x16x32_bf16 v[124:127], v[142:145], v[180:183], v[124:127]
	v_mfma_f32_16x16x32_bf16 v[116:119], v[150:153], v[180:183], v[116:119]
	v_mfma_f32_16x16x32_bf16 v[108:111], v[142:145], v[188:191], v[108:111]
	v_mfma_f32_16x16x32_bf16 v[100:103], v[150:153], v[188:191], v[100:103]
	v_mfma_f32_16x16x32_bf16 v[92:95], v[142:145], v[204:207], v[92:95]
	v_mfma_f32_16x16x32_bf16 v[84:87], v[150:153], v[204:207], v[84:87]
	v_mfma_f32_16x16x32_bf16 v[76:79], v[142:145], v[216:219], v[76:79]
	v_mfma_f32_16x16x32_bf16 v[68:71], v[150:153], v[216:219], v[68:71]
	v_mfma_f32_16x16x32_bf16 v[124:127], v[146:149], v[184:187], v[124:127]
	v_mfma_f32_16x16x32_bf16 v[116:119], v[154:157], v[184:187], v[116:119]
	v_mfma_f32_16x16x32_bf16 v[108:111], v[146:149], v[192:195], v[108:111]
	v_mfma_f32_16x16x32_bf16 v[100:103], v[154:157], v[192:195], v[100:103]
	v_mfma_f32_16x16x32_bf16 v[92:95], v[146:149], v[212:215], v[92:95]
	v_mfma_f32_16x16x32_bf16 v[84:87], v[154:157], v[212:215], v[84:87]
	v_mfma_f32_16x16x32_bf16 v[76:79], v[146:149], v[220:223], v[76:79]
	v_mfma_f32_16x16x32_bf16 v[68:71], v[154:157], v[220:223], v[68:71]
	v_mfma_f32_16x16x32_bf16 v[120:123], v[164:167], v[180:183], v[120:123]
	v_mfma_f32_16x16x32_bf16 v[112:115], v[172:175], v[180:183], v[112:115]
	v_mfma_f32_16x16x32_bf16 v[104:107], v[164:167], v[188:191], v[104:107]
	v_mfma_f32_16x16x32_bf16 v[96:99], v[172:175], v[188:191], v[96:99]
	v_mfma_f32_16x16x32_bf16 v[88:91], v[164:167], v[204:207], v[88:91]
	v_mfma_f32_16x16x32_bf16 v[80:83], v[172:175], v[204:207], v[80:83]
	v_mfma_f32_16x16x32_bf16 v[72:75], v[164:167], v[216:219], v[72:75]
	v_mfma_f32_16x16x32_bf16 v[64:67], v[172:175], v[216:219], v[64:67]
	v_mfma_f32_16x16x32_bf16 v[120:123], v[168:171], v[184:187], v[120:123]
	v_mfma_f32_16x16x32_bf16 v[112:115], v[176:179], v[184:187], v[112:115]
	v_mfma_f32_16x16x32_bf16 v[104:107], v[168:171], v[192:195], v[104:107]
	v_mfma_f32_16x16x32_bf16 v[96:99], v[176:179], v[192:195], v[96:99]
	v_mfma_f32_16x16x32_bf16 v[88:91], v[168:171], v[212:215], v[88:91]
	v_mfma_f32_16x16x32_bf16 v[80:83], v[176:179], v[212:215], v[80:83]
	v_mfma_f32_16x16x32_bf16 v[72:75], v[168:171], v[220:223], v[72:75]
	v_mfma_f32_16x16x32_bf16 v[64:67], v[176:179], v[220:223], v[64:67]
	s_barrier
	s_add_i32 s52, s52, s22
	v_lshl_add_u64 v[158:159], s[48:49], 0, v[196:197]
	s_mov_b32 m0, s52
	ds_read_b128 v[180:183], v141 offset:16384
	ds_read_b128 v[184:187], v141 offset:17408
	ds_read_b128 v[188:191], v141 offset:18432
	ds_read_b128 v[192:195], v141 offset:19456
	ds_read_b128 v[204:207], v141 offset:20480
	ds_read_b128 v[212:215], v141 offset:21504
	ds_read_b128 v[216:219], v141 offset:22528
	ds_read_b128 v[220:223], v141 offset:23552
	global_load_lds_dwordx4 v[158:159], off
	s_add_i32 m0, s52, 0x2000
	s_add_u32 s52, s48, 0x40000
	v_lshl_add_u64 v[232:233], s[48:49], 0, v[128:129]
	s_addc_u32 s53, s49, 0
	s_add_i32 s54, s54, s22
	global_load_lds_dwordx4 v[232:233], off
	v_lshl_add_u64 v[234:235], s[52:53], 0, v[196:197]
	s_mov_b32 m0, s54
	v_lshl_add_u64 v[236:237], s[50:51], 0, v[130:131]
	global_load_lds_dwordx4 v[234:235], off
	v_lshl_add_u64 v[234:235], s[52:53], 0, v[128:129]
	s_add_i32 m0, s54, 0x2000
	s_nop 0
	global_load_lds_dwordx4 v[234:235], off
	v_lshl_add_u64 v[234:235], s[50:51], 0, v[132:133]
	s_mov_b32 m0, s24
	s_nop 0
	global_load_lds_dwordx4 v[234:235], off
	s_mov_b32 m0, s25
	s_nop 0
	global_load_lds_dwordx4 v[236:237], off
	s_waitcnt vmcnt(8)
	s_cmp_eq_u32 s96, 0
	s_cbranch_scc1 .Lgl9
	s_waitcnt lgkmcnt(0)
.Lgl9:
	s_barrier
	s_waitcnt lgkmcnt(0)
	v_mfma_f32_16x16x32_bf16 v[60:63], v[142:145], v[180:183], v[60:63]
	v_mfma_f32_16x16x32_bf16 v[52:55], v[150:153], v[180:183], v[52:55]
	v_mfma_f32_16x16x32_bf16 v[44:47], v[142:145], v[188:191], v[44:47]
	v_mfma_f32_16x16x32_bf16 v[36:39], v[150:153], v[188:191], v[36:39]
	v_mfma_f32_16x16x32_bf16 v[28:31], v[142:145], v[204:207], v[28:31]
	v_mfma_f32_16x16x32_bf16 v[20:23], v[150:153], v[204:207], v[20:23]
	v_mfma_f32_16x16x32_bf16 v[12:15], v[142:145], v[216:219], v[12:15]
	v_mfma_f32_16x16x32_bf16 v[4:7], v[150:153], v[216:219], v[4:7]
	v_mfma_f32_16x16x32_bf16 v[60:63], v[146:149], v[184:187], v[60:63]
	v_mfma_f32_16x16x32_bf16 v[52:55], v[154:157], v[184:187], v[52:55]
	v_mfma_f32_16x16x32_bf16 v[44:47], v[146:149], v[192:195], v[44:47]
	v_mfma_f32_16x16x32_bf16 v[36:39], v[154:157], v[192:195], v[36:39]
	v_mfma_f32_16x16x32_bf16 v[28:31], v[146:149], v[212:215], v[28:31]
	v_mfma_f32_16x16x32_bf16 v[20:23], v[154:157], v[212:215], v[20:23]
	v_mfma_f32_16x16x32_bf16 v[12:15], v[146:149], v[220:223], v[12:15]
	v_mfma_f32_16x16x32_bf16 v[4:7], v[154:157], v[220:223], v[4:7]
	v_mfma_f32_16x16x32_bf16 v[56:59], v[164:167], v[180:183], v[56:59]
	v_mfma_f32_16x16x32_bf16 v[48:51], v[172:175], v[180:183], v[48:51]
	v_mfma_f32_16x16x32_bf16 v[40:43], v[164:167], v[188:191], v[40:43]
	v_mfma_f32_16x16x32_bf16 v[32:35], v[172:175], v[188:191], v[32:35]
	v_mfma_f32_16x16x32_bf16 v[24:27], v[164:167], v[204:207], v[24:27]
	v_mfma_f32_16x16x32_bf16 v[16:19], v[172:175], v[204:207], v[16:19]
	v_mfma_f32_16x16x32_bf16 v[8:11], v[164:167], v[216:219], v[8:11]
	v_mfma_f32_16x16x32_bf16 v[0:3], v[172:175], v[216:219], v[0:3]
	v_mfma_f32_16x16x32_bf16 v[56:59], v[168:171], v[184:187], v[56:59]
	v_mfma_f32_16x16x32_bf16 v[48:51], v[176:179], v[184:187], v[48:51]
	v_mfma_f32_16x16x32_bf16 v[40:43], v[168:171], v[192:195], v[40:43]
	v_mfma_f32_16x16x32_bf16 v[32:35], v[176:179], v[192:195], v[32:35]
	v_mfma_f32_16x16x32_bf16 v[24:27], v[168:171], v[212:215], v[24:27]
	v_mfma_f32_16x16x32_bf16 v[16:19], v[176:179], v[212:215], v[16:19]
	v_mfma_f32_16x16x32_bf16 v[8:11], v[168:171], v[220:223], v[8:11]
	v_mfma_f32_16x16x32_bf16 v[0:3], v[176:179], v[220:223], v[0:3]
	s_barrier
	s_add_i32 s52, 0, 0x18000
	s_add_i32 s53, 0, 0x1c000
	v_add_u32_e32 v154, s52, v139
	v_add_u32_e32 v176, s53, v139
	ds_read_b128 v[142:145], v154
	ds_read_b128 v[146:149], v154 offset:1024
	ds_read_b128 v[150:153], v154 offset:2048
	ds_read_b128 v[154:157], v154 offset:3072
	ds_read_b128 v[164:167], v176
	ds_read_b128 v[168:171], v176 offset:1024
	ds_read_b128 v[172:175], v176 offset:2048
	ds_read_b128 v[176:179], v176 offset:3072
	s_add_u32 s50, s50, 0x40000
	s_addc_u32 s51, s51, 0
	s_mov_b32 m0, s26
	v_lshl_add_u64 v[238:239], s[50:51], 0, v[132:133]
	ds_read_b128 v[180:183], v141 offset:32768
	ds_read_b128 v[184:187], v141 offset:33792
	ds_read_b128 v[188:191], v141 offset:34816
	ds_read_b128 v[192:195], v141 offset:35840
	ds_read_b128 v[204:207], v141 offset:36864
	ds_read_b128 v[212:215], v141 offset:37888
	ds_read_b128 v[216:219], v141 offset:38912
	ds_read_b128 v[220:223], v141 offset:39936
	global_load_lds_dwordx4 v[238:239], off
	v_lshl_add_u64 v[238:239], s[50:51], 0, v[130:131]
	s_mov_b32 m0, s27
	s_nop 0
	global_load_lds_dwordx4 v[238:239], off
	s_waitcnt vmcnt(8)
	s_cmp_eq_u32 s96, 0
	s_cbranch_scc1 .Lgl10
	s_waitcnt lgkmcnt(0)
.Lgl10:
	s_barrier
	s_waitcnt lgkmcnt(0)
	v_mfma_f32_16x16x32_bf16 v[124:127], v[142:145], v[180:183], v[124:127]
	v_mfma_f32_16x16x32_bf16 v[116:119], v[150:153], v[180:183], v[116:119]
	v_mfma_f32_16x16x32_bf16 v[108:111], v[142:145], v[188:191], v[108:111]
	v_mfma_f32_16x16x32_bf16 v[100:103], v[150:153], v[188:191], v[100:103]
	v_mfma_f32_16x16x32_bf16 v[92:95], v[142:145], v[204:207], v[92:95]
	v_mfma_f32_16x16x32_bf16 v[84:87], v[150:153], v[204:207], v[84:87]
	v_mfma_f32_16x16x32_bf16 v[76:79], v[142:145], v[216:219], v[76:79]
	v_mfma_f32_16x16x32_bf16 v[68:71], v[150:153], v[216:219], v[68:71]
	v_mfma_f32_16x16x32_bf16 v[124:127], v[146:149], v[184:187], v[124:127]
	v_mfma_f32_16x16x32_bf16 v[116:119], v[154:157], v[184:187], v[116:119]
	v_mfma_f32_16x16x32_bf16 v[108:111], v[146:149], v[192:195], v[108:111]
	v_mfma_f32_16x16x32_bf16 v[100:103], v[154:157], v[192:195], v[100:103]
	v_mfma_f32_16x16x32_bf16 v[92:95], v[146:149], v[212:215], v[92:95]
	v_mfma_f32_16x16x32_bf16 v[84:87], v[154:157], v[212:215], v[84:87]
	v_mfma_f32_16x16x32_bf16 v[76:79], v[146:149], v[220:223], v[76:79]
	v_mfma_f32_16x16x32_bf16 v[68:71], v[154:157], v[220:223], v[68:71]
	v_mfma_f32_16x16x32_bf16 v[120:123], v[164:167], v[180:183], v[120:123]
	v_mfma_f32_16x16x32_bf16 v[112:115], v[172:175], v[180:183], v[112:115]
	v_mfma_f32_16x16x32_bf16 v[104:107], v[164:167], v[188:191], v[104:107]
	v_mfma_f32_16x16x32_bf16 v[96:99], v[172:175], v[188:191], v[96:99]
	v_mfma_f32_16x16x32_bf16 v[88:91], v[164:167], v[204:207], v[88:91]
	v_mfma_f32_16x16x32_bf16 v[80:83], v[172:175], v[204:207], v[80:83]
	v_mfma_f32_16x16x32_bf16 v[72:75], v[164:167], v[216:219], v[72:75]
	v_mfma_f32_16x16x32_bf16 v[64:67], v[172:175], v[216:219], v[64:67]
	v_mfma_f32_16x16x32_bf16 v[120:123], v[168:171], v[184:187], v[120:123]
	v_mfma_f32_16x16x32_bf16 v[112:115], v[176:179], v[184:187], v[112:115]
	v_mfma_f32_16x16x32_bf16 v[104:107], v[168:171], v[192:195], v[104:107]
	v_mfma_f32_16x16x32_bf16 v[96:99], v[176:179], v[192:195], v[96:99]
	v_mfma_f32_16x16x32_bf16 v[88:91], v[168:171], v[212:215], v[88:91]
	v_mfma_f32_16x16x32_bf16 v[80:83], v[176:179], v[212:215], v[80:83]
	v_mfma_f32_16x16x32_bf16 v[72:75], v[168:171], v[220:223], v[72:75]
	v_mfma_f32_16x16x32_bf16 v[64:67], v[176:179], v[220:223], v[64:67]
	s_barrier
	s_add_i32 s50, s52, s22
	v_lshl_add_u64 v[158:159], v[158:159], 0, s[10:11]
	s_mov_b32 m0, s50
	ds_read_b128 v[180:183], v141 offset:49152
	ds_read_b128 v[184:187], v141 offset:50176
	ds_read_b128 v[188:191], v141 offset:51200
	ds_read_b128 v[192:195], v141 offset:52224
	ds_read_b128 v[204:207], v141 offset:53248
	ds_read_b128 v[212:215], v141 offset:54272
	ds_read_b128 v[216:219], v141 offset:55296
	ds_read_b128 v[220:223], v141 offset:56320
	global_load_lds_dwordx4 v[158:159], off
	s_add_i32 m0, s50, 0x2000
	s_add_u32 s48, s48, 0x40080
	v_lshl_add_u64 v[158:159], v[232:233], 0, s[10:11]
	s_addc_u32 s49, s49, 0
	s_add_i32 s50, s53, s22
	global_load_lds_dwordx4 v[158:159], off
	v_lshl_add_u64 v[158:159], s[48:49], 0, v[196:197]
	s_mov_b32 m0, s50
	s_nop 0
	global_load_lds_dwordx4 v[158:159], off
	v_lshl_add_u64 v[158:159], s[48:49], 0, v[128:129]
	s_add_i32 m0, s50, 0x2000
	s_nop 0
	global_load_lds_dwordx4 v[158:159], off
	v_lshl_add_u64 v[158:159], v[234:235], 0, s[10:11]
	s_mov_b32 m0, s4
	s_nop 0
	global_load_lds_dwordx4 v[158:159], off
	v_lshl_add_u64 v[158:159], v[236:237], 0, s[10:11]
	s_mov_b32 m0, s28
	s_nop 0
	global_load_lds_dwordx4 v[158:159], off
	s_waitcnt vmcnt(8)
	s_cmp_eq_u32 s96, 0
	s_cbranch_scc1 .Lgl11
	s_waitcnt lgkmcnt(0)
.Lgl11:
	s_barrier
	s_waitcnt lgkmcnt(0)
	v_mfma_f32_16x16x32_bf16 v[60:63], v[142:145], v[180:183], v[60:63]
	v_mfma_f32_16x16x32_bf16 v[52:55], v[150:153], v[180:183], v[52:55]
	v_mfma_f32_16x16x32_bf16 v[44:47], v[142:145], v[188:191], v[44:47]
	v_mfma_f32_16x16x32_bf16 v[36:39], v[150:153], v[188:191], v[36:39]
	v_mfma_f32_16x16x32_bf16 v[28:31], v[142:145], v[204:207], v[28:31]
	v_mfma_f32_16x16x32_bf16 v[20:23], v[150:153], v[204:207], v[20:23]
	v_mfma_f32_16x16x32_bf16 v[12:15], v[142:145], v[216:219], v[12:15]
	v_mfma_f32_16x16x32_bf16 v[4:7], v[150:153], v[216:219], v[4:7]
	v_mfma_f32_16x16x32_bf16 v[60:63], v[146:149], v[184:187], v[60:63]
	v_mfma_f32_16x16x32_bf16 v[52:55], v[154:157], v[184:187], v[52:55]
	v_mfma_f32_16x16x32_bf16 v[44:47], v[146:149], v[192:195], v[44:47]
	v_mfma_f32_16x16x32_bf16 v[36:39], v[154:157], v[192:195], v[36:39]
	v_mfma_f32_16x16x32_bf16 v[28:31], v[146:149], v[212:215], v[28:31]
	v_mfma_f32_16x16x32_bf16 v[20:23], v[154:157], v[212:215], v[20:23]
	v_mfma_f32_16x16x32_bf16 v[12:15], v[146:149], v[220:223], v[12:15]
	v_mfma_f32_16x16x32_bf16 v[4:7], v[154:157], v[220:223], v[4:7]
	v_mfma_f32_16x16x32_bf16 v[56:59], v[164:167], v[180:183], v[56:59]
	v_mfma_f32_16x16x32_bf16 v[48:51], v[172:175], v[180:183], v[48:51]
	v_mfma_f32_16x16x32_bf16 v[40:43], v[164:167], v[188:191], v[40:43]
	v_mfma_f32_16x16x32_bf16 v[32:35], v[172:175], v[188:191], v[32:35]
	v_mfma_f32_16x16x32_bf16 v[24:27], v[164:167], v[204:207], v[24:27]
	v_mfma_f32_16x16x32_bf16 v[16:19], v[172:175], v[204:207], v[16:19]
	v_mfma_f32_16x16x32_bf16 v[8:11], v[164:167], v[216:219], v[8:11]
	v_mfma_f32_16x16x32_bf16 v[0:3], v[172:175], v[216:219], v[0:3]
	v_mfma_f32_16x16x32_bf16 v[56:59], v[168:171], v[184:187], v[56:59]
	v_mfma_f32_16x16x32_bf16 v[48:51], v[176:179], v[184:187], v[48:51]
	v_mfma_f32_16x16x32_bf16 v[40:43], v[168:171], v[192:195], v[40:43]
	v_mfma_f32_16x16x32_bf16 v[32:35], v[176:179], v[192:195], v[32:35]
	v_mfma_f32_16x16x32_bf16 v[24:27], v[168:171], v[212:215], v[24:27]
	v_mfma_f32_16x16x32_bf16 v[16:19], v[176:179], v[212:215], v[16:19]
	v_mfma_f32_16x16x32_bf16 v[8:11], v[168:171], v[220:223], v[8:11]
	v_mfma_f32_16x16x32_bf16 v[0:3], v[176:179], v[220:223], v[0:3]
	s_barrier
	s_add_i32 s45, s45, 2
	s_add_u32 s46, s46, 0x100
	s_addc_u32 s47, s47, 0
	s_add_u32 s36, s36, 0x100
	s_addc_u32 s37, s37, 0
	s_cmp_gt_u32 s45, 13
	s_cbranch_scc0 .LBB0_799
	s_and_b64 vcc, exec, s[14:15]
	s_cbranch_vccz .LBB0_802
	s_barrier

.LBB0_823:
	s_add_u32 s41, s46, s36
	s_addc_u32 s58, s47, 0
	s_add_u32 s37, s41, 0x100
	s_addc_u32 s54, s58, 0
	s_and_b64 s[52:53], s[50:51], exec
	s_cselect_b32 s55, s17, s54
	s_cselect_b32 s54, s34, s37
	s_add_u32 s36, s44, s36
	s_addc_u32 s37, s45, 0
	s_add_u32 s52, s36, 0x100
	s_addc_u32 s53, s37, 0
	s_add_i32 s67, 0, 0x10000
	s_and_b64 s[36:37], s[50:51], exec
	s_cselect_b32 s57, s15, s53
	s_cselect_b32 s56, s35, s52
	s_add_i32 s51, 0, 0x14000
	s_add_u32 s60, s41, 0x10080
	s_addc_u32 s61, s58, 0
	s_add_i32 s66, s67, s21
	s_add_i32 m0, s24, 0xc000
	s_add_i32 s69, s24, 0xe000
	s_add_i32 s63, s66, 0x2000
	v_add_u32_e32 v134, s67, v137
	s_add_u32 s58, s56, 0x10000
	ds_read_b128 v[140:143], v134
	ds_read_b128 v[144:147], v134 offset:1024
	ds_read_b128 v[148:151], v134 offset:2048
	ds_read_b128 v[152:155], v134 offset:3072
	v_add_u32_e32 v134, s51, v137
	s_addc_u32 s59, s57, 0
	s_add_i32 s65, s51, s21
	ds_read_b128 v[156:159], v134
	ds_read_b128 v[164:167], v134 offset:1024
	ds_read_b128 v[168:171], v134 offset:2048
	ds_read_b128 v[172:175], v134 offset:3072
	s_add_i32 s64, s65, 0x2000
	s_add_i32 s62, 0, 0x18000
	s_add_i32 s41, 0, 0x1c000
	s_add_u32 s52, s54, 0x10000
	s_addc_u32 s53, s55, 0
	s_add_i32 s37, s62, s21
	s_add_i32 s36, s37, 0x2000
	s_add_u32 s50, s56, 0x10080
	s_addc_u32 s51, s57, 0
	s_add_i32 s68, s41, s21
	s_add_i32 s67, s68, 0x2000
	v_lshl_add_u64 v[134:135], s[60:61], 0, v[128:129]
	ds_read_b128 v[176:179], v139
	ds_read_b128 v[180:183], v139 offset:1024
	ds_read_b128 v[184:187], v139 offset:2048
	ds_read_b128 v[188:191], v139 offset:3072
	ds_read_b128 v[192:195], v139 offset:4096
	ds_read_b128 v[204:207], v139 offset:5120
	ds_read_b128 v[212:215], v139 offset:6144
	ds_read_b128 v[216:219], v139 offset:7168
	global_load_lds_dwordx4 v[134:135], off
	v_lshl_add_u64 v[134:135], s[60:61], 0, v[130:131]
	s_mov_b32 m0, s69
	s_nop 0
	global_load_lds_dwordx4 v[134:135], off
	s_waitcnt vmcnt(8)
	s_cmp_eq_u32 s96, 0
	s_cbranch_scc1 .Lgl12
	s_waitcnt lgkmcnt(0)
.Lgl12:
	s_barrier
	s_waitcnt lgkmcnt(0)
	v_mfma_f32_16x16x32_bf16 v[124:127], v[140:143], v[176:179], v[124:127]
	v_mfma_f32_16x16x32_bf16 v[120:123], v[148:151], v[176:179], v[120:123]
	v_mfma_f32_16x16x32_bf16 v[116:119], v[140:143], v[184:187], v[116:119]
	v_mfma_f32_16x16x32_bf16 v[108:111], v[148:151], v[184:187], v[108:111]
	v_mfma_f32_16x16x32_bf16 v[100:103], v[140:143], v[192:195], v[100:103]
	v_mfma_f32_16x16x32_bf16 v[92:95], v[148:151], v[192:195], v[92:95]
	v_mfma_f32_16x16x32_bf16 v[84:87], v[140:143], v[212:215], v[84:87]
	v_mfma_f32_16x16x32_bf16 v[76:79], v[148:151], v[212:215], v[76:79]
	v_mfma_f32_16x16x32_bf16 v[124:127], v[144:147], v[180:183], v[124:127]
	v_mfma_f32_16x16x32_bf16 v[120:123], v[152:155], v[180:183], v[120:123]
	v_mfma_f32_16x16x32_bf16 v[116:119], v[144:147], v[188:191], v[116:119]
	v_mfma_f32_16x16x32_bf16 v[108:111], v[152:155], v[188:191], v[108:111]
	v_mfma_f32_16x16x32_bf16 v[100:103], v[144:147], v[204:207], v[100:103]
	v_mfma_f32_16x16x32_bf16 v[92:95], v[152:155], v[204:207], v[92:95]
	v_mfma_f32_16x16x32_bf16 v[84:87], v[144:147], v[216:219], v[84:87]
	v_mfma_f32_16x16x32_bf16 v[76:79], v[152:155], v[216:219], v[76:79]
	v_mfma_f32_16x16x32_bf16 v[112:115], v[156:159], v[176:179], v[112:115]
	v_mfma_f32_16x16x32_bf16 v[104:107], v[168:171], v[176:179], v[104:107]
	v_mfma_f32_16x16x32_bf16 v[96:99], v[156:159], v[184:187], v[96:99]
	v_mfma_f32_16x16x32_bf16 v[88:91], v[168:171], v[184:187], v[88:91]
	v_mfma_f32_16x16x32_bf16 v[80:83], v[156:159], v[192:195], v[80:83]
	v_mfma_f32_16x16x32_bf16 v[72:75], v[168:171], v[192:195], v[72:75]
	v_mfma_f32_16x16x32_bf16 v[68:71], v[156:159], v[212:215], v[68:71]
	v_mfma_f32_16x16x32_bf16 v[64:67], v[168:171], v[212:215], v[64:67]
	v_mfma_f32_16x16x32_bf16 v[112:115], v[164:167], v[180:183], v[112:115]
	v_mfma_f32_16x16x32_bf16 v[104:107], v[172:175], v[180:183], v[104:107]
	v_mfma_f32_16x16x32_bf16 v[96:99], v[164:167], v[188:191], v[96:99]
	v_mfma_f32_16x16x32_bf16 v[88:91], v[172:175], v[188:191], v[88:91]
	v_mfma_f32_16x16x32_bf16 v[80:83], v[164:167], v[204:207], v[80:83]
	v_mfma_f32_16x16x32_bf16 v[72:75], v[172:175], v[204:207], v[72:75]
	v_mfma_f32_16x16x32_bf16 v[68:71], v[164:167], v[216:219], v[68:71]
	v_mfma_f32_16x16x32_bf16 v[64:67], v[172:175], v[216:219], v[64:67]
	s_barrier
	s_mov_b32 m0, s66
	v_lshl_add_u64 v[134:135], s[56:57], 0, v[196:197]
	ds_read_b128 v[176:179], v139 offset:16384
	ds_read_b128 v[180:183], v139 offset:17408
	ds_read_b128 v[184:187], v139 offset:18432
	ds_read_b128 v[188:191], v139 offset:19456
	ds_read_b128 v[192:195], v139 offset:20480
	ds_read_b128 v[204:207], v139 offset:21504
	ds_read_b128 v[212:215], v139 offset:22528
	ds_read_b128 v[216:219], v139 offset:23552
	global_load_lds_dwordx4 v[134:135], off
	v_lshl_add_u64 v[220:221], s[56:57], 0, v[132:133]
	s_mov_b32 m0, s63
	v_lshl_add_u64 v[222:223], s[58:59], 0, v[196:197]
	global_load_lds_dwordx4 v[220:221], off
	s_mov_b32 m0, s65
	v_lshl_add_u64 v[232:233], s[54:55], 0, v[130:131]
	global_load_lds_dwordx4 v[222:223], off
	v_lshl_add_u64 v[222:223], s[58:59], 0, v[132:133]
	s_mov_b32 m0, s64
	s_nop 0
	global_load_lds_dwordx4 v[222:223], off
	v_lshl_add_u64 v[222:223], s[54:55], 0, v[128:129]
	s_mov_b32 m0, s24
	s_nop 0
	global_load_lds_dwordx4 v[222:223], off
	s_mov_b32 m0, s25
	s_nop 0
	global_load_lds_dwordx4 v[232:233], off
	s_waitcnt vmcnt(8)
	s_cmp_eq_u32 s96, 0
	s_cbranch_scc1 .Lgl13
	s_waitcnt lgkmcnt(0)
.Lgl13:
	s_barrier
	s_waitcnt lgkmcnt(0)
	v_mfma_f32_16x16x32_bf16 v[60:63], v[140:143], v[176:179], v[60:63]
	v_mfma_f32_16x16x32_bf16 v[56:59], v[148:151], v[176:179], v[56:59]
	v_mfma_f32_16x16x32_bf16 v[52:55], v[140:143], v[184:187], v[52:55]
	v_mfma_f32_16x16x32_bf16 v[44:47], v[148:151], v[184:187], v[44:47]
	v_mfma_f32_16x16x32_bf16 v[36:39], v[140:143], v[192:195], v[36:39]
	v_mfma_f32_16x16x32_bf16 v[28:31], v[148:151], v[192:195], v[28:31]
	v_mfma_f32_16x16x32_bf16 v[20:23], v[140:143], v[212:215], v[20:23]
	v_mfma_f32_16x16x32_bf16 v[12:15], v[148:151], v[212:215], v[12:15]
	v_mfma_f32_16x16x32_bf16 v[60:63], v[144:147], v[180:183], v[60:63]
	v_mfma_f32_16x16x32_bf16 v[56:59], v[152:155], v[180:183], v[56:59]
	v_mfma_f32_16x16x32_bf16 v[52:55], v[144:147], v[188:191], v[52:55]
	v_mfma_f32_16x16x32_bf16 v[44:47], v[152:155], v[188:191], v[44:47]
	v_mfma_f32_16x16x32_bf16 v[36:39], v[144:147], v[204:207], v[36:39]
	v_mfma_f32_16x16x32_bf16 v[28:31], v[152:155], v[204:207], v[28:31]
	v_mfma_f32_16x16x32_bf16 v[20:23], v[144:147], v[216:219], v[20:23]
	v_mfma_f32_16x16x32_bf16 v[12:15], v[152:155], v[216:219], v[12:15]
	v_mfma_f32_16x16x32_bf16 v[48:51], v[156:159], v[176:179], v[48:51]
	v_mfma_f32_16x16x32_bf16 v[40:43], v[168:171], v[176:179], v[40:43]
	v_mfma_f32_16x16x32_bf16 v[32:35], v[156:159], v[184:187], v[32:35]
	v_mfma_f32_16x16x32_bf16 v[24:27], v[168:171], v[184:187], v[24:27]
	v_mfma_f32_16x16x32_bf16 v[16:19], v[156:159], v[192:195], v[16:19]
	v_mfma_f32_16x16x32_bf16 v[8:11], v[168:171], v[192:195], v[8:11]
	v_mfma_f32_16x16x32_bf16 v[4:7], v[156:159], v[212:215], v[4:7]
	v_mfma_f32_16x16x32_bf16 v[0:3], v[168:171], v[212:215], v[0:3]
	v_mfma_f32_16x16x32_bf16 v[48:51], v[164:167], v[180:183], v[48:51]
	v_mfma_f32_16x16x32_bf16 v[40:43], v[172:175], v[180:183], v[40:43]
	v_mfma_f32_16x16x32_bf16 v[32:35], v[164:167], v[188:191], v[32:35]
	v_mfma_f32_16x16x32_bf16 v[24:27], v[172:175], v[188:191], v[24:27]
	v_mfma_f32_16x16x32_bf16 v[16:19], v[164:167], v[204:207], v[16:19]
	v_mfma_f32_16x16x32_bf16 v[8:11], v[172:175], v[204:207], v[8:11]
	v_mfma_f32_16x16x32_bf16 v[4:7], v[164:167], v[216:219], v[4:7]
	v_mfma_f32_16x16x32_bf16 v[0:3], v[172:175], v[216:219], v[0:3]
	s_barrier
	v_add_u32_e32 v152, s62, v137
	v_add_u32_e32 v172, s41, v137
	ds_read_b128 v[140:143], v152
	ds_read_b128 v[144:147], v152 offset:1024
	ds_read_b128 v[148:151], v152 offset:2048
	ds_read_b128 v[152:155], v152 offset:3072
	ds_read_b128 v[156:159], v172
	ds_read_b128 v[164:167], v172 offset:1024
	ds_read_b128 v[168:171], v172 offset:2048
	ds_read_b128 v[172:175], v172 offset:3072
	s_mov_b32 m0, s26
	v_lshl_add_u64 v[234:235], s[52:53], 0, v[128:129]
	ds_read_b128 v[176:179], v139 offset:32768
	ds_read_b128 v[180:183], v139 offset:33792
	ds_read_b128 v[184:187], v139 offset:34816
	ds_read_b128 v[188:191], v139 offset:35840
	ds_read_b128 v[192:195], v139 offset:36864
	ds_read_b128 v[204:207], v139 offset:37888
	ds_read_b128 v[212:215], v139 offset:38912
	ds_read_b128 v[216:219], v139 offset:39936
	global_load_lds_dwordx4 v[234:235], off
	v_lshl_add_u64 v[234:235], s[52:53], 0, v[130:131]
	s_mov_b32 m0, s27
	s_nop 0
	global_load_lds_dwordx4 v[234:235], off
	s_waitcnt vmcnt(8)
	s_cmp_eq_u32 s96, 0
	s_cbranch_scc1 .Lgl14
	s_waitcnt lgkmcnt(0)
.Lgl14:
	s_barrier
	s_waitcnt lgkmcnt(0)
	v_mfma_f32_16x16x32_bf16 v[124:127], v[140:143], v[176:179], v[124:127]
	v_mfma_f32_16x16x32_bf16 v[120:123], v[148:151], v[176:179], v[120:123]
	v_mfma_f32_16x16x32_bf16 v[116:119], v[140:143], v[184:187], v[116:119]
	v_mfma_f32_16x16x32_bf16 v[108:111], v[148:151], v[184:187], v[108:111]
	v_mfma_f32_16x16x32_bf16 v[100:103], v[140:143], v[192:195], v[100:103]
	v_mfma_f32_16x16x32_bf16 v[92:95], v[148:151], v[192:195], v[92:95]
	v_mfma_f32_16x16x32_bf16 v[84:87], v[140:143], v[212:215], v[84:87]
	v_mfma_f32_16x16x32_bf16 v[76:79], v[148:151], v[212:215], v[76:79]
	v_mfma_f32_16x16x32_bf16 v[124:127], v[144:147], v[180:183], v[124:127]
	v_mfma_f32_16x16x32_bf16 v[120:123], v[152:155], v[180:183], v[120:123]
	v_mfma_f32_16x16x32_bf16 v[116:119], v[144:147], v[188:191], v[116:119]
	v_mfma_f32_16x16x32_bf16 v[108:111], v[152:155], v[188:191], v[108:111]
	v_mfma_f32_16x16x32_bf16 v[100:103], v[144:147], v[204:207], v[100:103]
	v_mfma_f32_16x16x32_bf16 v[92:95], v[152:155], v[204:207], v[92:95]
	v_mfma_f32_16x16x32_bf16 v[84:87], v[144:147], v[216:219], v[84:87]
	v_mfma_f32_16x16x32_bf16 v[76:79], v[152:155], v[216:219], v[76:79]
	v_mfma_f32_16x16x32_bf16 v[112:115], v[156:159], v[176:179], v[112:115]
	v_mfma_f32_16x16x32_bf16 v[104:107], v[168:171], v[176:179], v[104:107]
	v_mfma_f32_16x16x32_bf16 v[96:99], v[156:159], v[184:187], v[96:99]
	v_mfma_f32_16x16x32_bf16 v[88:91], v[168:171], v[184:187], v[88:91]
	v_mfma_f32_16x16x32_bf16 v[80:83], v[156:159], v[192:195], v[80:83]
	v_mfma_f32_16x16x32_bf16 v[72:75], v[168:171], v[192:195], v[72:75]
	v_mfma_f32_16x16x32_bf16 v[68:71], v[156:159], v[212:215], v[68:71]
	v_mfma_f32_16x16x32_bf16 v[64:67], v[168:171], v[212:215], v[64:67]
	v_mfma_f32_16x16x32_bf16 v[112:115], v[164:167], v[180:183], v[112:115]
	v_mfma_f32_16x16x32_bf16 v[104:107], v[172:175], v[180:183], v[104:107]
	v_mfma_f32_16x16x32_bf16 v[96:99], v[164:167], v[188:191], v[96:99]
	v_mfma_f32_16x16x32_bf16 v[88:91], v[172:175], v[188:191], v[88:91]
	v_mfma_f32_16x16x32_bf16 v[80:83], v[164:167], v[204:207], v[80:83]
	v_mfma_f32_16x16x32_bf16 v[72:75], v[172:175], v[204:207], v[72:75]
	v_mfma_f32_16x16x32_bf16 v[68:71], v[164:167], v[216:219], v[68:71]
	v_mfma_f32_16x16x32_bf16 v[64:67], v[172:175], v[216:219], v[64:67]
	s_barrier
	s_mov_b32 m0, s37
	v_lshl_add_u64 v[134:135], v[134:135], 0, s[10:11]
	ds_read_b128 v[176:179], v139 offset:49152
	ds_read_b128 v[180:183], v139 offset:50176
	ds_read_b128 v[184:187], v139 offset:51200
	ds_read_b128 v[188:191], v139 offset:52224
	ds_read_b128 v[192:195], v139 offset:53248
	ds_read_b128 v[204:207], v139 offset:54272
	ds_read_b128 v[212:215], v139 offset:55296
	ds_read_b128 v[216:219], v139 offset:56320
	global_load_lds_dwordx4 v[134:135], off
	v_lshl_add_u64 v[134:135], v[220:221], 0, s[10:11]
	s_mov_b32 m0, s36
	s_nop 0
	global_load_lds_dwordx4 v[134:135], off
	v_lshl_add_u64 v[134:135], s[50:51], 0, v[196:197]
	s_mov_b32 m0, s68
	s_nop 0
	global_load_lds_dwordx4 v[134:135], off
	v_lshl_add_u64 v[134:135], s[50:51], 0, v[132:133]
	s_mov_b32 m0, s67
	s_nop 0
	global_load_lds_dwordx4 v[134:135], off
	v_lshl_add_u64 v[134:135], v[222:223], 0, s[10:11]
	s_mov_b32 m0, s4
	s_nop 0
	global_load_lds_dwordx4 v[134:135], off
	v_lshl_add_u64 v[134:135], v[232:233], 0, s[10:11]
	s_mov_b32 m0, s28
	s_nop 0
	global_load_lds_dwordx4 v[134:135], off
	s_waitcnt vmcnt(8)
	s_cmp_eq_u32 s96, 0
	s_cbranch_scc1 .Lgl15
	s_waitcnt lgkmcnt(0)
.Lgl15:
	s_barrier
	s_waitcnt lgkmcnt(0)
	v_mfma_f32_16x16x32_bf16 v[60:63], v[140:143], v[176:179], v[60:63]
	v_mfma_f32_16x16x32_bf16 v[56:59], v[148:151], v[176:179], v[56:59]
	v_mfma_f32_16x16x32_bf16 v[52:55], v[140:143], v[184:187], v[52:55]
	v_mfma_f32_16x16x32_bf16 v[44:47], v[148:151], v[184:187], v[44:47]
	v_mfma_f32_16x16x32_bf16 v[36:39], v[140:143], v[192:195], v[36:39]
	v_mfma_f32_16x16x32_bf16 v[28:31], v[148:151], v[192:195], v[28:31]
	v_mfma_f32_16x16x32_bf16 v[20:23], v[140:143], v[212:215], v[20:23]
	v_mfma_f32_16x16x32_bf16 v[12:15], v[148:151], v[212:215], v[12:15]
	v_mfma_f32_16x16x32_bf16 v[60:63], v[144:147], v[180:183], v[60:63]
	v_mfma_f32_16x16x32_bf16 v[56:59], v[152:155], v[180:183], v[56:59]
	v_mfma_f32_16x16x32_bf16 v[52:55], v[144:147], v[188:191], v[52:55]
	v_mfma_f32_16x16x32_bf16 v[44:47], v[152:155], v[188:191], v[44:47]
	v_mfma_f32_16x16x32_bf16 v[36:39], v[144:147], v[204:207], v[36:39]
	v_mfma_f32_16x16x32_bf16 v[28:31], v[152:155], v[204:207], v[28:31]
	v_mfma_f32_16x16x32_bf16 v[20:23], v[144:147], v[216:219], v[20:23]
	v_mfma_f32_16x16x32_bf16 v[12:15], v[152:155], v[216:219], v[12:15]
	v_mfma_f32_16x16x32_bf16 v[48:51], v[156:159], v[176:179], v[48:51]
	v_mfma_f32_16x16x32_bf16 v[40:43], v[168:171], v[176:179], v[40:43]
	v_mfma_f32_16x16x32_bf16 v[32:35], v[156:159], v[184:187], v[32:35]
	v_mfma_f32_16x16x32_bf16 v[24:27], v[168:171], v[184:187], v[24:27]
	v_mfma_f32_16x16x32_bf16 v[16:19], v[156:159], v[192:195], v[16:19]
	v_mfma_f32_16x16x32_bf16 v[8:11], v[168:171], v[192:195], v[8:11]
	v_mfma_f32_16x16x32_bf16 v[4:7], v[156:159], v[212:215], v[4:7]
	v_mfma_f32_16x16x32_bf16 v[0:3], v[168:171], v[212:215], v[0:3]
	v_mfma_f32_16x16x32_bf16 v[48:51], v[164:167], v[180:183], v[48:51]
	v_mfma_f32_16x16x32_bf16 v[40:43], v[172:175], v[180:183], v[40:43]
	v_mfma_f32_16x16x32_bf16 v[32:35], v[164:167], v[188:191], v[32:35]
	v_mfma_f32_16x16x32_bf16 v[24:27], v[172:175], v[188:191], v[24:27]
	v_mfma_f32_16x16x32_bf16 v[16:19], v[164:167], v[204:207], v[16:19]
	v_mfma_f32_16x16x32_bf16 v[8:11], v[172:175], v[204:207], v[8:11]
	v_mfma_f32_16x16x32_bf16 v[4:7], v[164:167], v[216:219], v[4:7]
	v_mfma_f32_16x16x32_bf16 v[0:3], v[172:175], v[216:219], v[0:3]
	s_barrier
	s_movk_i32 s36, 0x100
	s_andn2_b64 vcc, exec, s[48:49]
	s_mov_b64 s[50:51], -1
	s_mov_b64 s[48:49], 0
	s_cbranch_vccz .LBB0_823
	s_and_b64 vcc, exec, s[12:13]
	s_cbranch_vccz .LBB0_826
	s_barrier

.LBB0_882:
	s_or_b64 exec, exec, s[6:7]
	v_readfirstlane_b32 s96, v211
	s_lshr_b32 s96, s96, 8
	s_waitcnt lgkmcnt(0)
	v_mov_b32_e32 v0, v211
	s_mov_b32 s0, s94
	s_mov_b32 s1, s74
	v_readlane_b32 s2, v255, 31
	s_mov_b64 s[8:9], s[92:93]
	v_mov_b32_e32 v8, v211
	s_barrier
	s_cmpk_lt_i32 s1, 0x100
	v_readfirstlane_b32 s12, v8
	s_cbranch_scc0 .LBB0_910
	s_ashr_i32 s2, s1, 31
	s_lshr_b32 s3, s2, 29
	s_add_i32 s4, s1, s3
	s_and_b32 s3, s4, -8
	s_sub_i32 s3, s1, s3
	s_cmp_gt_i32 s3, -1
	s_mov_b64 s[6:7], -1
	s_cbranch_scc0 .LBB0_885
	s_lshl_b32 s14, s3, 5
	s_mov_b64 s[6:7], 0

.LBB0_903:
	s_add_u32 s40, s18, 0x100
	s_addc_u32 s41, s19, 0
	s_add_i32 s48, 0, 0x10000
	s_cmp_eq_u32 s47, 40
	s_cselect_b32 s45, s15, s41
	s_cselect_b32 s44, s14, s40
	s_cselect_b32 s43, s17, s46
	s_cselect_b32 s42, s16, s37
	s_add_i32 s49, 0, 0x14000
	v_add_u32_e32 v154, s48, v143
	v_add_u32_e32 v158, s49, v143
	ds_read_b128 v[138:141], v154
	ds_read_b128 v[146:149], v154 offset:1024
	ds_read_b128 v[150:153], v154 offset:2048
	ds_read_b128 v[154:157], v154 offset:3072
	ds_read_b128 v[164:167], v158
	ds_read_b128 v[168:171], v158 offset:1024
	ds_read_b128 v[172:175], v158 offset:2048
	ds_read_b128 v[176:179], v158 offset:3072
	v_lshl_add_u64 v[158:159], s[18:19], 0, v[134:135]
	s_add_i32 m0, s23, 0xc000
	ds_read_b128 v[180:183], v145
	ds_read_b128 v[184:187], v145 offset:1024
	ds_read_b128 v[188:191], v145 offset:2048
	ds_read_b128 v[192:195], v145 offset:3072
	ds_read_b128 v[204:207], v145 offset:4096
	ds_read_b128 v[212:215], v145 offset:5120
	ds_read_b128 v[216:219], v145 offset:6144
	ds_read_b128 v[220:223], v145 offset:7168
	global_load_lds_dwordx4 v[158:159], off
	v_lshl_add_u64 v[158:159], s[18:19], 0, v[136:137]
	s_add_i32 m0, s23, 0xe000
	s_nop 0
	global_load_lds_dwordx4 v[158:159], off
	s_waitcnt vmcnt(8)
	s_cmp_eq_u32 s96, 0
	s_cbranch_scc1 .Lgl16
	s_waitcnt lgkmcnt(0)
.Lgl16:
	s_barrier
	s_waitcnt lgkmcnt(0)
	v_mfma_f32_16x16x32_bf16 v[124:127], v[138:141], v[180:183], v[124:127]
	v_mfma_f32_16x16x32_bf16 v[120:123], v[150:153], v[180:183], v[120:123]
	v_mfma_f32_16x16x32_bf16 v[112:115], v[138:141], v[188:191], v[112:115]
	v_mfma_f32_16x16x32_bf16 v[104:107], v[150:153], v[188:191], v[104:107]
	v_mfma_f32_16x16x32_bf16 v[96:99], v[138:141], v[204:207], v[96:99]
	v_mfma_f32_16x16x32_bf16 v[88:91], v[150:153], v[204:207], v[88:91]
	v_mfma_f32_16x16x32_bf16 v[80:83], v[138:141], v[216:219], v[80:83]
	v_mfma_f32_16x16x32_bf16 v[72:75], v[150:153], v[216:219], v[72:75]
	v_mfma_f32_16x16x32_bf16 v[124:127], v[146:149], v[184:187], v[124:127]
	v_mfma_f32_16x16x32_bf16 v[120:123], v[154:157], v[184:187], v[120:123]
	v_mfma_f32_16x16x32_bf16 v[112:115], v[146:149], v[192:195], v[112:115]
	v_mfma_f32_16x16x32_bf16 v[104:107], v[154:157], v[192:195], v[104:107]
	v_mfma_f32_16x16x32_bf16 v[96:99], v[146:149], v[212:215], v[96:99]
	v_mfma_f32_16x16x32_bf16 v[88:91], v[154:157], v[212:215], v[88:91]
	v_mfma_f32_16x16x32_bf16 v[80:83], v[146:149], v[220:223], v[80:83]
	v_mfma_f32_16x16x32_bf16 v[72:75], v[154:157], v[220:223], v[72:75]
	v_mfma_f32_16x16x32_bf16 v[116:119], v[164:167], v[180:183], v[116:119]
	v_mfma_f32_16x16x32_bf16 v[108:111], v[172:175], v[180:183], v[108:111]
	v_mfma_f32_16x16x32_bf16 v[100:103], v[164:167], v[188:191], v[100:103]
	v_mfma_f32_16x16x32_bf16 v[92:95], v[172:175], v[188:191], v[92:95]
	v_mfma_f32_16x16x32_bf16 v[84:87], v[164:167], v[204:207], v[84:87]
	v_mfma_f32_16x16x32_bf16 v[76:79], v[172:175], v[204:207], v[76:79]
	v_mfma_f32_16x16x32_bf16 v[68:71], v[164:167], v[216:219], v[68:71]
	v_mfma_f32_16x16x32_bf16 v[64:67], v[172:175], v[216:219], v[64:67]
	v_mfma_f32_16x16x32_bf16 v[116:119], v[168:171], v[184:187], v[116:119]
	v_mfma_f32_16x16x32_bf16 v[108:111], v[176:179], v[184:187], v[108:111]
	v_mfma_f32_16x16x32_bf16 v[100:103], v[168:171], v[192:195], v[100:103]
	v_mfma_f32_16x16x32_bf16 v[92:95], v[176:179], v[192:195], v[92:95]
	v_mfma_f32_16x16x32_bf16 v[84:87], v[168:171], v[212:215], v[84:87]
	v_mfma_f32_16x16x32_bf16 v[76:79], v[176:179], v[212:215], v[76:79]
	v_mfma_f32_16x16x32_bf16 v[68:71], v[168:171], v[220:223], v[68:71]
	v_mfma_f32_16x16x32_bf16 v[64:67], v[176:179], v[220:223], v[64:67]
	s_barrier
	s_add_i32 s18, s48, s22
	v_lshl_add_u64 v[158:159], s[42:43], 0, v[196:197]
	s_mov_b32 m0, s18
	ds_read_b128 v[180:183], v145 offset:16384
	ds_read_b128 v[184:187], v145 offset:17408
	ds_read_b128 v[188:191], v145 offset:18432
	ds_read_b128 v[192:195], v145 offset:19456
	ds_read_b128 v[204:207], v145 offset:20480
	ds_read_b128 v[212:215], v145 offset:21504
	ds_read_b128 v[216:219], v145 offset:22528
	ds_read_b128 v[220:223], v145 offset:23552
	global_load_lds_dwordx4 v[158:159], off
	s_add_i32 m0, s18, 0x2000
	s_add_u32 s18, s42, 0xb0000
	v_lshl_add_u64 v[232:233], s[42:43], 0, v[132:133]
	s_addc_u32 s19, s43, 0
	s_add_i32 s48, s49, s22
	global_load_lds_dwordx4 v[232:233], off
	v_lshl_add_u64 v[234:235], s[18:19], 0, v[196:197]
	s_mov_b32 m0, s48
	v_lshl_add_u64 v[236:237], s[44:45], 0, v[130:131]
	global_load_lds_dwordx4 v[234:235], off
	v_lshl_add_u64 v[234:235], s[18:19], 0, v[132:133]
	s_add_i32 m0, s48, 0x2000
	s_nop 0
	global_load_lds_dwordx4 v[234:235], off
	v_lshl_add_u64 v[234:235], s[44:45], 0, v[128:129]
	s_mov_b32 m0, s23
	s_nop 0
	global_load_lds_dwordx4 v[234:235], off
	s_mov_b32 m0, s24
	s_nop 0
	global_load_lds_dwordx4 v[236:237], off
	s_waitcnt vmcnt(8)
	s_cmp_eq_u32 s96, 0
	s_cbranch_scc1 .Lgl17
	s_waitcnt lgkmcnt(0)
.Lgl17:
	s_barrier
	s_waitcnt lgkmcnt(0)
	v_mfma_f32_16x16x32_bf16 v[60:63], v[138:141], v[180:183], v[60:63]
	v_mfma_f32_16x16x32_bf16 v[56:59], v[150:153], v[180:183], v[56:59]
	v_mfma_f32_16x16x32_bf16 v[48:51], v[138:141], v[188:191], v[48:51]
	v_mfma_f32_16x16x32_bf16 v[40:43], v[150:153], v[188:191], v[40:43]
	v_mfma_f32_16x16x32_bf16 v[32:35], v[138:141], v[204:207], v[32:35]
	v_mfma_f32_16x16x32_bf16 v[24:27], v[150:153], v[204:207], v[24:27]
	v_mfma_f32_16x16x32_bf16 v[16:19], v[138:141], v[216:219], v[16:19]
	v_mfma_f32_16x16x32_bf16 v[8:11], v[150:153], v[216:219], v[8:11]
	v_mfma_f32_16x16x32_bf16 v[60:63], v[146:149], v[184:187], v[60:63]
	v_mfma_f32_16x16x32_bf16 v[56:59], v[154:157], v[184:187], v[56:59]
	v_mfma_f32_16x16x32_bf16 v[48:51], v[146:149], v[192:195], v[48:51]
	v_mfma_f32_16x16x32_bf16 v[40:43], v[154:157], v[192:195], v[40:43]
	v_mfma_f32_16x16x32_bf16 v[32:35], v[146:149], v[212:215], v[32:35]
	v_mfma_f32_16x16x32_bf16 v[24:27], v[154:157], v[212:215], v[24:27]
	v_mfma_f32_16x16x32_bf16 v[16:19], v[146:149], v[220:223], v[16:19]
	v_mfma_f32_16x16x32_bf16 v[8:11], v[154:157], v[220:223], v[8:11]
	v_mfma_f32_16x16x32_bf16 v[52:55], v[164:167], v[180:183], v[52:55]
	v_mfma_f32_16x16x32_bf16 v[44:47], v[172:175], v[180:183], v[44:47]
	v_mfma_f32_16x16x32_bf16 v[36:39], v[164:167], v[188:191], v[36:39]
	v_mfma_f32_16x16x32_bf16 v[28:31], v[172:175], v[188:191], v[28:31]
	v_mfma_f32_16x16x32_bf16 v[20:23], v[164:167], v[204:207], v[20:23]
	v_mfma_f32_16x16x32_bf16 v[12:15], v[172:175], v[204:207], v[12:15]
	v_mfma_f32_16x16x32_bf16 v[4:7], v[164:167], v[216:219], v[4:7]
	v_mfma_f32_16x16x32_bf16 v[0:3], v[172:175], v[216:219], v[0:3]
	v_mfma_f32_16x16x32_bf16 v[52:55], v[168:171], v[184:187], v[52:55]
	v_mfma_f32_16x16x32_bf16 v[44:47], v[176:179], v[184:187], v[44:47]
	v_mfma_f32_16x16x32_bf16 v[36:39], v[168:171], v[192:195], v[36:39]
	v_mfma_f32_16x16x32_bf16 v[28:31], v[176:179], v[192:195], v[28:31]
	v_mfma_f32_16x16x32_bf16 v[20:23], v[168:171], v[212:215], v[20:23]
	v_mfma_f32_16x16x32_bf16 v[12:15], v[176:179], v[212:215], v[12:15]
	v_mfma_f32_16x16x32_bf16 v[4:7], v[168:171], v[220:223], v[4:7]
	v_mfma_f32_16x16x32_bf16 v[0:3], v[176:179], v[220:223], v[0:3]
	s_barrier
	s_add_i32 s48, 0, 0x18000
	s_add_i32 s49, 0, 0x1c000
	v_add_u32_e32 v154, s48, v143
	v_add_u32_e32 v176, s49, v143
	ds_read_b128 v[138:141], v154
	ds_read_b128 v[146:149], v154 offset:1024
	ds_read_b128 v[150:153], v154 offset:2048
	ds_read_b128 v[154:157], v154 offset:3072
	ds_read_b128 v[164:167], v176
	ds_read_b128 v[168:171], v176 offset:1024
	ds_read_b128 v[172:175], v176 offset:2048
	ds_read_b128 v[176:179], v176 offset:3072
	s_add_u32 s18, s44, 0xb0000
	s_addc_u32 s19, s45, 0
	s_mov_b32 m0, s25
	v_lshl_add_u64 v[238:239], s[18:19], 0, v[128:129]
	ds_read_b128 v[180:183], v145 offset:32768
	ds_read_b128 v[184:187], v145 offset:33792
	ds_read_b128 v[188:191], v145 offset:34816
	ds_read_b128 v[192:195], v145 offset:35840
	ds_read_b128 v[204:207], v145 offset:36864
	ds_read_b128 v[212:215], v145 offset:37888
	ds_read_b128 v[216:219], v145 offset:38912
	ds_read_b128 v[220:223], v145 offset:39936
	global_load_lds_dwordx4 v[238:239], off
	v_lshl_add_u64 v[238:239], s[18:19], 0, v[130:131]
	s_mov_b32 m0, s26
	s_nop 0
	global_load_lds_dwordx4 v[238:239], off
	s_waitcnt vmcnt(8)
	s_cmp_eq_u32 s96, 0
	s_cbranch_scc1 .Lgl18
	s_waitcnt lgkmcnt(0)
.Lgl18:
	s_barrier
	s_waitcnt lgkmcnt(0)
	v_mfma_f32_16x16x32_bf16 v[124:127], v[138:141], v[180:183], v[124:127]
	v_mfma_f32_16x16x32_bf16 v[120:123], v[150:153], v[180:183], v[120:123]
	v_mfma_f32_16x16x32_bf16 v[112:115], v[138:141], v[188:191], v[112:115]
	v_mfma_f32_16x16x32_bf16 v[104:107], v[150:153], v[188:191], v[104:107]
	v_mfma_f32_16x16x32_bf16 v[96:99], v[138:141], v[204:207], v[96:99]
	v_mfma_f32_16x16x32_bf16 v[88:91], v[150:153], v[204:207], v[88:91]
	v_mfma_f32_16x16x32_bf16 v[80:83], v[138:141], v[216:219], v[80:83]
	v_mfma_f32_16x16x32_bf16 v[72:75], v[150:153], v[216:219], v[72:75]
	v_mfma_f32_16x16x32_bf16 v[124:127], v[146:149], v[184:187], v[124:127]
	v_mfma_f32_16x16x32_bf16 v[120:123], v[154:157], v[184:187], v[120:123]
	v_mfma_f32_16x16x32_bf16 v[112:115], v[146:149], v[192:195], v[112:115]
	v_mfma_f32_16x16x32_bf16 v[104:107], v[154:157], v[192:195], v[104:107]
	v_mfma_f32_16x16x32_bf16 v[96:99], v[146:149], v[212:215], v[96:99]
	v_mfma_f32_16x16x32_bf16 v[88:91], v[154:157], v[212:215], v[88:91]
	v_mfma_f32_16x16x32_bf16 v[80:83], v[146:149], v[220:223], v[80:83]
	v_mfma_f32_16x16x32_bf16 v[72:75], v[154:157], v[220:223], v[72:75]
	v_mfma_f32_16x16x32_bf16 v[116:119], v[164:167], v[180:183], v[116:119]
	v_mfma_f32_16x16x32_bf16 v[108:111], v[172:175], v[180:183], v[108:111]
	v_mfma_f32_16x16x32_bf16 v[100:103], v[164:167], v[188:191], v[100:103]
	v_mfma_f32_16x16x32_bf16 v[92:95], v[172:175], v[188:191], v[92:95]
	v_mfma_f32_16x16x32_bf16 v[84:87], v[164:167], v[204:207], v[84:87]
	v_mfma_f32_16x16x32_bf16 v[76:79], v[172:175], v[204:207], v[76:79]
	v_mfma_f32_16x16x32_bf16 v[68:71], v[164:167], v[216:219], v[68:71]
	v_mfma_f32_16x16x32_bf16 v[64:67], v[172:175], v[216:219], v[64:67]
	v_mfma_f32_16x16x32_bf16 v[116:119], v[168:171], v[184:187], v[116:119]
	v_mfma_f32_16x16x32_bf16 v[108:111], v[176:179], v[184:187], v[108:111]
	v_mfma_f32_16x16x32_bf16 v[100:103], v[168:171], v[192:195], v[100:103]
	v_mfma_f32_16x16x32_bf16 v[92:95], v[176:179], v[192:195], v[92:95]
	v_mfma_f32_16x16x32_bf16 v[84:87], v[168:171], v[212:215], v[84:87]
	v_mfma_f32_16x16x32_bf16 v[76:79], v[176:179], v[212:215], v[76:79]
	v_mfma_f32_16x16x32_bf16 v[68:71], v[168:171], v[220:223], v[68:71]
	v_mfma_f32_16x16x32_bf16 v[64:67], v[176:179], v[220:223], v[64:67]
	s_barrier
	s_add_i32 s18, s48, s22
	v_lshl_add_u64 v[158:159], v[158:159], 0, s[10:11]
	s_mov_b32 m0, s18
	ds_read_b128 v[180:183], v145 offset:49152
	ds_read_b128 v[184:187], v145 offset:50176
	ds_read_b128 v[188:191], v145 offset:51200
	ds_read_b128 v[192:195], v145 offset:52224
	ds_read_b128 v[204:207], v145 offset:53248
	ds_read_b128 v[212:215], v145 offset:54272
	ds_read_b128 v[216:219], v145 offset:55296
	ds_read_b128 v[220:223], v145 offset:56320
	global_load_lds_dwordx4 v[158:159], off
	s_add_i32 m0, s18, 0x2000
	s_add_u32 s18, s42, 0xb0080
	v_lshl_add_u64 v[158:159], v[232:233], 0, s[10:11]
	s_addc_u32 s19, s43, 0
	s_add_i32 s42, s49, s22
	global_load_lds_dwordx4 v[158:159], off
	v_lshl_add_u64 v[158:159], s[18:19], 0, v[196:197]
	s_mov_b32 m0, s42
	s_nop 0
	global_load_lds_dwordx4 v[158:159], off
	v_lshl_add_u64 v[158:159], s[18:19], 0, v[132:133]
	s_add_i32 m0, s42, 0x2000
	s_nop 0
	global_load_lds_dwordx4 v[158:159], off
	v_lshl_add_u64 v[158:159], v[234:235], 0, s[10:11]
	s_mov_b32 m0, s27
	s_nop 0
	global_load_lds_dwordx4 v[158:159], off
	v_lshl_add_u64 v[158:159], v[236:237], 0, s[10:11]
	s_mov_b32 m0, s28
	s_nop 0
	global_load_lds_dwordx4 v[158:159], off
	s_waitcnt vmcnt(8)
	s_cmp_eq_u32 s96, 0
	s_cbranch_scc1 .Lgl19
	s_waitcnt lgkmcnt(0)
.Lgl19:
	s_barrier
	s_waitcnt lgkmcnt(0)
	v_mfma_f32_16x16x32_bf16 v[60:63], v[138:141], v[180:183], v[60:63]
	v_mfma_f32_16x16x32_bf16 v[56:59], v[150:153], v[180:183], v[56:59]
	v_mfma_f32_16x16x32_bf16 v[48:51], v[138:141], v[188:191], v[48:51]
	v_mfma_f32_16x16x32_bf16 v[40:43], v[150:153], v[188:191], v[40:43]
	v_mfma_f32_16x16x32_bf16 v[32:35], v[138:141], v[204:207], v[32:35]
	v_mfma_f32_16x16x32_bf16 v[24:27], v[150:153], v[204:207], v[24:27]
	v_mfma_f32_16x16x32_bf16 v[16:19], v[138:141], v[216:219], v[16:19]
	v_mfma_f32_16x16x32_bf16 v[8:11], v[150:153], v[216:219], v[8:11]
	v_mfma_f32_16x16x32_bf16 v[60:63], v[146:149], v[184:187], v[60:63]
	v_mfma_f32_16x16x32_bf16 v[56:59], v[154:157], v[184:187], v[56:59]
	v_mfma_f32_16x16x32_bf16 v[48:51], v[146:149], v[192:195], v[48:51]
	v_mfma_f32_16x16x32_bf16 v[40:43], v[154:157], v[192:195], v[40:43]
	v_mfma_f32_16x16x32_bf16 v[32:35], v[146:149], v[212:215], v[32:35]
	v_mfma_f32_16x16x32_bf16 v[24:27], v[154:157], v[212:215], v[24:27]
	v_mfma_f32_16x16x32_bf16 v[16:19], v[146:149], v[220:223], v[16:19]
	v_mfma_f32_16x16x32_bf16 v[8:11], v[154:157], v[220:223], v[8:11]
	v_mfma_f32_16x16x32_bf16 v[52:55], v[164:167], v[180:183], v[52:55]
	v_mfma_f32_16x16x32_bf16 v[44:47], v[172:175], v[180:183], v[44:47]
	v_mfma_f32_16x16x32_bf16 v[36:39], v[164:167], v[188:191], v[36:39]
	v_mfma_f32_16x16x32_bf16 v[28:31], v[172:175], v[188:191], v[28:31]
	v_mfma_f32_16x16x32_bf16 v[20:23], v[164:167], v[204:207], v[20:23]
	v_mfma_f32_16x16x32_bf16 v[12:15], v[172:175], v[204:207], v[12:15]
	v_mfma_f32_16x16x32_bf16 v[4:7], v[164:167], v[216:219], v[4:7]
	v_mfma_f32_16x16x32_bf16 v[0:3], v[172:175], v[216:219], v[0:3]
	v_mfma_f32_16x16x32_bf16 v[52:55], v[168:171], v[184:187], v[52:55]
	v_mfma_f32_16x16x32_bf16 v[44:47], v[176:179], v[184:187], v[44:47]
	v_mfma_f32_16x16x32_bf16 v[36:39], v[168:171], v[192:195], v[36:39]
	v_mfma_f32_16x16x32_bf16 v[28:31], v[176:179], v[192:195], v[28:31]
	v_mfma_f32_16x16x32_bf16 v[20:23], v[168:171], v[212:215], v[20:23]
	v_mfma_f32_16x16x32_bf16 v[12:15], v[176:179], v[212:215], v[12:15]
	v_mfma_f32_16x16x32_bf16 v[4:7], v[168:171], v[220:223], v[4:7]
	v_mfma_f32_16x16x32_bf16 v[0:3], v[176:179], v[220:223], v[0:3]
	s_barrier
	s_add_i32 s47, s47, 2
	s_add_u32 s37, s37, 0x100
	s_addc_u32 s46, s46, 0
	s_cmp_gt_u32 s47, 41
	s_mov_b64 s[18:19], s[40:41]
	s_cbranch_scc0 .LBB0_903
	s_and_b64 vcc, exec, s[12:13]
	s_cbranch_vccz .LBB0_906
	s_barrier

.LBB0_962:
	s_or_b64 exec, exec, s[6:7]
	v_readfirstlane_b32 s96, v211
	s_lshr_b32 s96, s96, 8
	s_waitcnt lgkmcnt(0)
	v_mov_b32_e32 v0, v211
	s_mov_b32 s54, s94
	s_mov_b32 s55, s74
	v_readlane_b32 s0, v255, 31
	s_mov_b64 s[14:15], s[92:93]
	s_barrier
	s_add_u32 s16, s14, 0x1e00000
	s_addc_u32 s17, s15, 0
	s_add_u32 s56, s14, 0x1a90000
	s_addc_u32 s57, s15, 0
	s_mov_b32 s59, s0
	s_cmp_gt_i32 s0, 0
	s_mov_b64 s[6:7], -1
	s_cbranch_scc0 .LBB0_1017
	v_mov_b32_e32 v155, v211
	s_cmpk_gt_i32 s55, 0xff
	v_readfirstlane_b32 s58, v155
	s_cbranch_scc1 .LBB0_1016
	s_ashr_i32 s0, s55, 31
	s_lshr_b32 s1, s0, 29
	s_add_i32 s3, s55, s1
	s_and_b32 s1, s3, -8
	s_sub_i32 s1, s55, s1
	s_cmp_gt_i32 s1, -1
	s_cbranch_scc0 .LBB0_966
	s_lshl_b32 s2, s1, 5
	s_mov_b64 s[6:7], 0

.LBB0_978:
	s_add_u32 s31, s6, s48
	s_addc_u32 s34, s7, s49
	s_add_u32 s31, s31, 0x100
	s_addc_u32 s34, s34, 0
	s_add_u32 s35, s26, s48
	s_addc_u32 s36, s27, s49
	s_add_i32 s37, 0, 0x10000
	s_cmpk_eq_i32 s48, 0x700
	s_cselect_b32 s53, s13, s34
	s_cselect_b32 s52, s28, s31
	v_add_u32_e32 v145, s37, v143
	s_cselect_b32 s51, s9, s36
	s_cselect_b32 s50, s29, s35
	s_add_i32 s31, 0, 0x14000
	ds_read_b128 v[146:149], v145
	ds_read_b128 v[150:153], v145 offset:1024
	ds_read_b128 v[156:159], v145 offset:2048
	ds_read_b128 v[164:167], v145 offset:3072
	v_add_u32_e32 v145, s31, v143
	ds_read_b128 v[168:171], v145
	ds_read_b128 v[172:175], v145 offset:1024
	ds_read_b128 v[176:179], v145 offset:2048
	ds_read_b128 v[180:183], v145 offset:3072
	v_lshl_add_u64 v[236:237], v[138:139], 0, s[48:49]
	s_add_i32 m0, s2, 0xc000
	ds_read_b128 v[184:187], v144
	ds_read_b128 v[188:191], v144 offset:1024
	ds_read_b128 v[192:195], v144 offset:2048
	ds_read_b128 v[204:207], v144 offset:3072
	ds_read_b128 v[212:215], v144 offset:4096
	ds_read_b128 v[216:219], v144 offset:5120
	ds_read_b128 v[220:223], v144 offset:6144
	ds_read_b128 v[232:235], v144 offset:7168
	global_load_lds_dwordx4 v[236:237], off
	v_lshl_add_u64 v[236:237], v[140:141], 0, s[48:49]
	s_add_i32 m0, s2, 0xe000
	s_nop 0
	global_load_lds_dwordx4 v[236:237], off
	s_waitcnt vmcnt(8)
	s_cmp_eq_u32 s96, 0
	s_cbranch_scc1 .Lgl20
	s_waitcnt lgkmcnt(0)
.Lgl20:
	s_barrier
	s_waitcnt lgkmcnt(0)
	v_mfma_f32_16x16x32_bf16 v[124:127], v[146:149], v[184:187], v[124:127]
	v_mfma_f32_16x16x32_bf16 v[120:123], v[156:159], v[184:187], v[120:123]
	v_mfma_f32_16x16x32_bf16 v[108:111], v[146:149], v[192:195], v[108:111]
	v_mfma_f32_16x16x32_bf16 v[104:107], v[156:159], v[192:195], v[104:107]
	v_mfma_f32_16x16x32_bf16 v[92:95], v[146:149], v[212:215], v[92:95]
	v_mfma_f32_16x16x32_bf16 v[88:91], v[156:159], v[212:215], v[88:91]
	v_mfma_f32_16x16x32_bf16 v[76:79], v[146:149], v[220:223], v[76:79]
	v_mfma_f32_16x16x32_bf16 v[72:75], v[156:159], v[220:223], v[72:75]
	v_mfma_f32_16x16x32_bf16 v[124:127], v[150:153], v[188:191], v[124:127]
	v_mfma_f32_16x16x32_bf16 v[120:123], v[164:167], v[188:191], v[120:123]
	v_mfma_f32_16x16x32_bf16 v[108:111], v[150:153], v[204:207], v[108:111]
	v_mfma_f32_16x16x32_bf16 v[104:107], v[164:167], v[204:207], v[104:107]
	v_mfma_f32_16x16x32_bf16 v[92:95], v[150:153], v[216:219], v[92:95]
	v_mfma_f32_16x16x32_bf16 v[88:91], v[164:167], v[216:219], v[88:91]
	v_mfma_f32_16x16x32_bf16 v[76:79], v[150:153], v[232:235], v[76:79]
	v_mfma_f32_16x16x32_bf16 v[72:75], v[164:167], v[232:235], v[72:75]
	v_mfma_f32_16x16x32_bf16 v[116:119], v[168:171], v[184:187], v[116:119]
	v_mfma_f32_16x16x32_bf16 v[112:115], v[176:179], v[184:187], v[112:115]
	v_mfma_f32_16x16x32_bf16 v[100:103], v[168:171], v[192:195], v[100:103]
	v_mfma_f32_16x16x32_bf16 v[96:99], v[176:179], v[192:195], v[96:99]
	v_mfma_f32_16x16x32_bf16 v[84:87], v[168:171], v[212:215], v[84:87]
	v_mfma_f32_16x16x32_bf16 v[80:83], v[176:179], v[212:215], v[80:83]
	v_mfma_f32_16x16x32_bf16 v[68:71], v[168:171], v[220:223], v[68:71]
	v_mfma_f32_16x16x32_bf16 v[64:67], v[176:179], v[220:223], v[64:67]
	v_mfma_f32_16x16x32_bf16 v[116:119], v[172:175], v[188:191], v[116:119]
	v_mfma_f32_16x16x32_bf16 v[112:115], v[180:183], v[188:191], v[112:115]
	v_mfma_f32_16x16x32_bf16 v[100:103], v[172:175], v[204:207], v[100:103]
	v_mfma_f32_16x16x32_bf16 v[96:99], v[180:183], v[204:207], v[96:99]
	v_mfma_f32_16x16x32_bf16 v[84:87], v[172:175], v[216:219], v[84:87]
	v_mfma_f32_16x16x32_bf16 v[80:83], v[180:183], v[216:219], v[80:83]
	v_mfma_f32_16x16x32_bf16 v[68:71], v[172:175], v[232:235], v[68:71]
	v_mfma_f32_16x16x32_bf16 v[64:67], v[180:183], v[232:235], v[64:67]
	s_barrier
	s_add_i32 s34, s37, s1
	v_lshl_add_u64 v[236:237], s[50:51], 0, v[196:197]
	s_mov_b32 m0, s34
	ds_read_b128 v[184:187], v144 offset:16384
	ds_read_b128 v[188:191], v144 offset:17408
	ds_read_b128 v[192:195], v144 offset:18432
	ds_read_b128 v[204:207], v144 offset:19456
	ds_read_b128 v[212:215], v144 offset:20480
	ds_read_b128 v[216:219], v144 offset:21504
	ds_read_b128 v[220:223], v144 offset:22528
	ds_read_b128 v[232:235], v144 offset:23552
	global_load_lds_dwordx4 v[236:237], off
	s_add_i32 m0, s34, 0x2000
	s_add_u32 s34, s50, 0x40000
	v_lshl_add_u64 v[238:239], s[50:51], 0, v[132:133]
	s_addc_u32 s35, s51, 0
	s_add_i32 s31, s31, s1
	global_load_lds_dwordx4 v[238:239], off
	v_lshl_add_u64 v[240:241], s[34:35], 0, v[196:197]
	s_mov_b32 m0, s31
	v_lshl_add_u64 v[242:243], s[52:53], 0, v[130:131]
	global_load_lds_dwordx4 v[240:241], off
	v_lshl_add_u64 v[240:241], s[34:35], 0, v[132:133]
	s_add_i32 m0, s31, 0x2000
	s_nop 0
	global_load_lds_dwordx4 v[240:241], off
	v_lshl_add_u64 v[240:241], s[52:53], 0, v[128:129]
	s_mov_b32 m0, s2
	s_nop 0
	global_load_lds_dwordx4 v[240:241], off
	s_mov_b32 m0, s19
	s_nop 0
	global_load_lds_dwordx4 v[242:243], off
	s_waitcnt vmcnt(8)
	s_cmp_eq_u32 s96, 0
	s_cbranch_scc1 .Lgl21
	s_waitcnt lgkmcnt(0)
.Lgl21:
	s_barrier
	s_waitcnt lgkmcnt(0)
	v_mfma_f32_16x16x32_bf16 v[60:63], v[146:149], v[184:187], v[60:63]
	v_mfma_f32_16x16x32_bf16 v[56:59], v[156:159], v[184:187], v[56:59]
	v_mfma_f32_16x16x32_bf16 v[44:47], v[146:149], v[192:195], v[44:47]
	v_mfma_f32_16x16x32_bf16 v[40:43], v[156:159], v[192:195], v[40:43]
	v_mfma_f32_16x16x32_bf16 v[28:31], v[146:149], v[212:215], v[28:31]
	v_mfma_f32_16x16x32_bf16 v[24:27], v[156:159], v[212:215], v[24:27]
	v_mfma_f32_16x16x32_bf16 v[12:15], v[146:149], v[220:223], v[12:15]
	v_mfma_f32_16x16x32_bf16 v[8:11], v[156:159], v[220:223], v[8:11]
	v_mfma_f32_16x16x32_bf16 v[60:63], v[150:153], v[188:191], v[60:63]
	v_mfma_f32_16x16x32_bf16 v[56:59], v[164:167], v[188:191], v[56:59]
	v_mfma_f32_16x16x32_bf16 v[44:47], v[150:153], v[204:207], v[44:47]
	v_mfma_f32_16x16x32_bf16 v[40:43], v[164:167], v[204:207], v[40:43]
	v_mfma_f32_16x16x32_bf16 v[28:31], v[150:153], v[216:219], v[28:31]
	v_mfma_f32_16x16x32_bf16 v[24:27], v[164:167], v[216:219], v[24:27]
	v_mfma_f32_16x16x32_bf16 v[12:15], v[150:153], v[232:235], v[12:15]
	v_mfma_f32_16x16x32_bf16 v[8:11], v[164:167], v[232:235], v[8:11]
	v_mfma_f32_16x16x32_bf16 v[52:55], v[168:171], v[184:187], v[52:55]
	v_mfma_f32_16x16x32_bf16 v[48:51], v[176:179], v[184:187], v[48:51]
	v_mfma_f32_16x16x32_bf16 v[36:39], v[168:171], v[192:195], v[36:39]
	v_mfma_f32_16x16x32_bf16 v[32:35], v[176:179], v[192:195], v[32:35]
	v_mfma_f32_16x16x32_bf16 v[20:23], v[168:171], v[212:215], v[20:23]
	v_mfma_f32_16x16x32_bf16 v[16:19], v[176:179], v[212:215], v[16:19]
	v_mfma_f32_16x16x32_bf16 v[4:7], v[168:171], v[220:223], v[4:7]
	v_mfma_f32_16x16x32_bf16 v[0:3], v[176:179], v[220:223], v[0:3]
	v_mfma_f32_16x16x32_bf16 v[52:55], v[172:175], v[188:191], v[52:55]
	v_mfma_f32_16x16x32_bf16 v[48:51], v[180:183], v[188:191], v[48:51]
	v_mfma_f32_16x16x32_bf16 v[36:39], v[172:175], v[204:207], v[36:39]
	v_mfma_f32_16x16x32_bf16 v[32:35], v[180:183], v[204:207], v[32:35]
	v_mfma_f32_16x16x32_bf16 v[20:23], v[172:175], v[216:219], v[20:23]
	v_mfma_f32_16x16x32_bf16 v[16:19], v[180:183], v[216:219], v[16:19]
	v_mfma_f32_16x16x32_bf16 v[4:7], v[172:175], v[232:235], v[4:7]
	v_mfma_f32_16x16x32_bf16 v[0:3], v[180:183], v[232:235], v[0:3]
	s_barrier
	s_add_i32 s31, 0, 0x18000
	v_add_u32_e32 v145, s31, v143
	s_add_i32 s36, 0, 0x1c000
	ds_read_b128 v[146:149], v145
	ds_read_b128 v[150:153], v145 offset:1024
	ds_read_b128 v[156:159], v145 offset:2048
	ds_read_b128 v[164:167], v145 offset:3072
	v_add_u32_e32 v145, s36, v143
	ds_read_b128 v[168:171], v145
	ds_read_b128 v[172:175], v145 offset:1024
	ds_read_b128 v[176:179], v145 offset:2048
	ds_read_b128 v[180:183], v145 offset:3072
	s_add_u32 s34, s52, 0x40000
	s_addc_u32 s35, s53, 0
	s_mov_b32 m0, s20
	v_lshl_add_u64 v[244:245], s[34:35], 0, v[128:129]
	ds_read_b128 v[184:187], v144 offset:32768
	ds_read_b128 v[188:191], v144 offset:33792
	ds_read_b128 v[192:195], v144 offset:34816
	ds_read_b128 v[204:207], v144 offset:35840
	ds_read_b128 v[212:215], v144 offset:36864
	ds_read_b128 v[216:219], v144 offset:37888
	ds_read_b128 v[220:223], v144 offset:38912
	ds_read_b128 v[232:235], v144 offset:39936
	global_load_lds_dwordx4 v[244:245], off
	v_lshl_add_u64 v[244:245], s[34:35], 0, v[130:131]
	s_mov_b32 m0, s21
	s_nop 0
	global_load_lds_dwordx4 v[244:245], off
	s_waitcnt vmcnt(8)
	s_cmp_eq_u32 s96, 0
	s_cbranch_scc1 .Lgl22
	s_waitcnt lgkmcnt(0)
.Lgl22:
	s_barrier
	s_waitcnt lgkmcnt(0)
	v_mfma_f32_16x16x32_bf16 v[124:127], v[146:149], v[184:187], v[124:127]
	v_mfma_f32_16x16x32_bf16 v[120:123], v[156:159], v[184:187], v[120:123]
	v_mfma_f32_16x16x32_bf16 v[108:111], v[146:149], v[192:195], v[108:111]
	v_mfma_f32_16x16x32_bf16 v[104:107], v[156:159], v[192:195], v[104:107]
	v_mfma_f32_16x16x32_bf16 v[92:95], v[146:149], v[212:215], v[92:95]
	v_mfma_f32_16x16x32_bf16 v[88:91], v[156:159], v[212:215], v[88:91]
	v_mfma_f32_16x16x32_bf16 v[76:79], v[146:149], v[220:223], v[76:79]
	v_mfma_f32_16x16x32_bf16 v[72:75], v[156:159], v[220:223], v[72:75]
	v_mfma_f32_16x16x32_bf16 v[124:127], v[150:153], v[188:191], v[124:127]
	v_mfma_f32_16x16x32_bf16 v[120:123], v[164:167], v[188:191], v[120:123]
	v_mfma_f32_16x16x32_bf16 v[108:111], v[150:153], v[204:207], v[108:111]
	v_mfma_f32_16x16x32_bf16 v[104:107], v[164:167], v[204:207], v[104:107]
	v_mfma_f32_16x16x32_bf16 v[92:95], v[150:153], v[216:219], v[92:95]
	v_mfma_f32_16x16x32_bf16 v[88:91], v[164:167], v[216:219], v[88:91]
	v_mfma_f32_16x16x32_bf16 v[76:79], v[150:153], v[232:235], v[76:79]
	v_mfma_f32_16x16x32_bf16 v[72:75], v[164:167], v[232:235], v[72:75]
	v_mfma_f32_16x16x32_bf16 v[116:119], v[168:171], v[184:187], v[116:119]
	v_mfma_f32_16x16x32_bf16 v[112:115], v[176:179], v[184:187], v[112:115]
	v_mfma_f32_16x16x32_bf16 v[100:103], v[168:171], v[192:195], v[100:103]
	v_mfma_f32_16x16x32_bf16 v[96:99], v[176:179], v[192:195], v[96:99]
	v_mfma_f32_16x16x32_bf16 v[84:87], v[168:171], v[212:215], v[84:87]
	v_mfma_f32_16x16x32_bf16 v[80:83], v[176:179], v[212:215], v[80:83]
	v_mfma_f32_16x16x32_bf16 v[68:71], v[168:171], v[220:223], v[68:71]
	v_mfma_f32_16x16x32_bf16 v[64:67], v[176:179], v[220:223], v[64:67]
	v_mfma_f32_16x16x32_bf16 v[116:119], v[172:175], v[188:191], v[116:119]
	v_mfma_f32_16x16x32_bf16 v[112:115], v[180:183], v[188:191], v[112:115]
	v_mfma_f32_16x16x32_bf16 v[100:103], v[172:175], v[204:207], v[100:103]
	v_mfma_f32_16x16x32_bf16 v[96:99], v[180:183], v[204:207], v[96:99]
	v_mfma_f32_16x16x32_bf16 v[84:87], v[172:175], v[216:219], v[84:87]
	v_mfma_f32_16x16x32_bf16 v[80:83], v[180:183], v[216:219], v[80:83]
	v_mfma_f32_16x16x32_bf16 v[68:71], v[172:175], v[232:235], v[68:71]
	v_mfma_f32_16x16x32_bf16 v[64:67], v[180:183], v[232:235], v[64:67]
	s_barrier
	s_add_i32 s31, s31, s1
	v_lshl_add_u64 v[236:237], v[236:237], 0, s[10:11]
	s_mov_b32 m0, s31
	ds_read_b128 v[184:187], v144 offset:49152
	ds_read_b128 v[188:191], v144 offset:50176
	ds_read_b128 v[192:195], v144 offset:51200
	ds_read_b128 v[204:207], v144 offset:52224
	ds_read_b128 v[212:215], v144 offset:53248
	ds_read_b128 v[216:219], v144 offset:54272
	ds_read_b128 v[220:223], v144 offset:55296
	ds_read_b128 v[232:235], v144 offset:56320
	global_load_lds_dwordx4 v[236:237], off
	s_add_i32 m0, s31, 0x2000
	s_add_u32 s34, s50, 0x40080
	v_lshl_add_u64 v[236:237], v[238:239], 0, s[10:11]
	s_addc_u32 s35, s51, 0
	s_add_i32 s31, s36, s1
	global_load_lds_dwordx4 v[236:237], off
	v_lshl_add_u64 v[236:237], s[34:35], 0, v[196:197]
	s_mov_b32 m0, s31
	s_nop 0
	global_load_lds_dwordx4 v[236:237], off
	v_lshl_add_u64 v[236:237], s[34:35], 0, v[132:133]
	s_add_i32 m0, s31, 0x2000
	s_nop 0
	global_load_lds_dwordx4 v[236:237], off
	v_lshl_add_u64 v[236:237], v[240:241], 0, s[10:11]
	s_mov_b32 m0, s22
	s_nop 0
	global_load_lds_dwordx4 v[236:237], off
	v_lshl_add_u64 v[236:237], v[242:243], 0, s[10:11]
	s_mov_b32 m0, s23
	s_nop 0
	global_load_lds_dwordx4 v[236:237], off
	s_waitcnt vmcnt(8)
	s_cmp_eq_u32 s96, 0
	s_cbranch_scc1 .Lgl23
	s_waitcnt lgkmcnt(0)
.Lgl23:
	s_barrier
	s_waitcnt lgkmcnt(0)
	v_mfma_f32_16x16x32_bf16 v[60:63], v[146:149], v[184:187], v[60:63]
	v_mfma_f32_16x16x32_bf16 v[56:59], v[156:159], v[184:187], v[56:59]
	v_mfma_f32_16x16x32_bf16 v[44:47], v[146:149], v[192:195], v[44:47]
	v_mfma_f32_16x16x32_bf16 v[40:43], v[156:159], v[192:195], v[40:43]
	v_mfma_f32_16x16x32_bf16 v[28:31], v[146:149], v[212:215], v[28:31]
	v_mfma_f32_16x16x32_bf16 v[24:27], v[156:159], v[212:215], v[24:27]
	v_mfma_f32_16x16x32_bf16 v[12:15], v[146:149], v[220:223], v[12:15]
	v_mfma_f32_16x16x32_bf16 v[8:11], v[156:159], v[220:223], v[8:11]
	v_mfma_f32_16x16x32_bf16 v[60:63], v[150:153], v[188:191], v[60:63]
	v_mfma_f32_16x16x32_bf16 v[56:59], v[164:167], v[188:191], v[56:59]
	v_mfma_f32_16x16x32_bf16 v[44:47], v[150:153], v[204:207], v[44:47]
	v_mfma_f32_16x16x32_bf16 v[40:43], v[164:167], v[204:207], v[40:43]
	v_mfma_f32_16x16x32_bf16 v[28:31], v[150:153], v[216:219], v[28:31]
	v_mfma_f32_16x16x32_bf16 v[24:27], v[164:167], v[216:219], v[24:27]
	v_mfma_f32_16x16x32_bf16 v[12:15], v[150:153], v[232:235], v[12:15]
	v_mfma_f32_16x16x32_bf16 v[8:11], v[164:167], v[232:235], v[8:11]
	v_mfma_f32_16x16x32_bf16 v[52:55], v[168:171], v[184:187], v[52:55]
	v_mfma_f32_16x16x32_bf16 v[48:51], v[176:179], v[184:187], v[48:51]
	v_mfma_f32_16x16x32_bf16 v[36:39], v[168:171], v[192:195], v[36:39]
	v_mfma_f32_16x16x32_bf16 v[32:35], v[176:179], v[192:195], v[32:35]
	v_mfma_f32_16x16x32_bf16 v[20:23], v[168:171], v[212:215], v[20:23]
	v_mfma_f32_16x16x32_bf16 v[16:19], v[176:179], v[212:215], v[16:19]
	v_mfma_f32_16x16x32_bf16 v[4:7], v[168:171], v[220:223], v[4:7]
	v_mfma_f32_16x16x32_bf16 v[0:3], v[176:179], v[220:223], v[0:3]
	v_mfma_f32_16x16x32_bf16 v[52:55], v[172:175], v[188:191], v[52:55]
	v_mfma_f32_16x16x32_bf16 v[48:51], v[180:183], v[188:191], v[48:51]
	v_mfma_f32_16x16x32_bf16 v[36:39], v[172:175], v[204:207], v[36:39]
	v_mfma_f32_16x16x32_bf16 v[32:35], v[180:183], v[204:207], v[32:35]
	v_mfma_f32_16x16x32_bf16 v[20:23], v[172:175], v[216:219], v[20:23]
	v_mfma_f32_16x16x32_bf16 v[16:19], v[180:183], v[216:219], v[16:19]
	v_mfma_f32_16x16x32_bf16 v[4:7], v[172:175], v[232:235], v[4:7]
	v_mfma_f32_16x16x32_bf16 v[0:3], v[180:183], v[232:235], v[0:3]
	s_barrier
	s_add_i32 s30, s30, 2
	s_add_u32 s48, s48, 0x100
	s_addc_u32 s49, s49, 0
	s_cmp_gt_u32 s30, 13
	s_cbranch_scc0 .LBB0_978
	s_add_u32 s48, s26, 0xffffff00
	s_addc_u32 s49, s27, -1
	s_andn2_b64 vcc, exec, s[40:41]
	s_cbranch_vccnz .LBB0_981
	v_mov_b32_e32 v0, 0
	s_mov_b32 s42, s8
	s_mov_b32 s18, s12
	s_mov_b64 s[6:7], s[46:47]
	s_mov_b32 s24, s25
	v_mov_b32_e32 v1, v0
	v_mov_b32_e32 v2, v0
	v_mov_b32_e32 v3, v0
	v_mov_b32_e32 v4, v0
	v_mov_b32_e32 v5, v0
	v_mov_b32_e32 v6, v0
	v_mov_b32_e32 v7, v0
	v_mov_b32_e32 v16, v0
	v_mov_b32_e32 v17, v0
	v_mov_b32_e32 v18, v0
	v_mov_b32_e32 v19, v0
	v_mov_b32_e32 v20, v0
	v_mov_b32_e32 v21, v0
	v_mov_b32_e32 v22, v0
	v_mov_b32_e32 v23, v0
	v_mov_b32_e32 v32, v0
	v_mov_b32_e32 v33, v0
	v_mov_b32_e32 v34, v0
	v_mov_b32_e32 v35, v0
	v_mov_b32_e32 v36, v0
	v_mov_b32_e32 v37, v0
	v_mov_b32_e32 v38, v0
	v_mov_b32_e32 v39, v0
	v_mov_b32_e32 v48, v0
	v_mov_b32_e32 v49, v0
	v_mov_b32_e32 v50, v0
	v_mov_b32_e32 v51, v0
	v_mov_b32_e32 v52, v0
	v_mov_b32_e32 v53, v0
	v_mov_b32_e32 v54, v0
	v_mov_b32_e32 v55, v0
	v_mov_b32_e32 v8, v0
	v_mov_b32_e32 v9, v0
	v_mov_b32_e32 v10, v0
	v_mov_b32_e32 v11, v0
	v_mov_b32_e32 v12, v0
	v_mov_b32_e32 v13, v0
	v_mov_b32_e32 v14, v0
	v_mov_b32_e32 v15, v0
	v_mov_b32_e32 v24, v0
	v_mov_b32_e32 v25, v0
	v_mov_b32_e32 v26, v0
	v_mov_b32_e32 v27, v0
	v_mov_b32_e32 v28, v0
	v_mov_b32_e32 v29, v0
	v_mov_b32_e32 v30, v0
	v_mov_b32_e32 v31, v0
	v_mov_b32_e32 v40, v0
	v_mov_b32_e32 v41, v0
	v_mov_b32_e32 v42, v0
	v_mov_b32_e32 v43, v0
	v_mov_b32_e32 v44, v0
	v_mov_b32_e32 v45, v0
	v_mov_b32_e32 v46, v0
	v_mov_b32_e32 v47, v0
	v_mov_b32_e32 v56, v0
	v_mov_b32_e32 v57, v0
	v_mov_b32_e32 v58, v0
	v_mov_b32_e32 v59, v0
	v_mov_b32_e32 v60, v0
	v_mov_b32_e32 v61, v0
	v_mov_b32_e32 v62, v0
	v_mov_b32_e32 v63, v0
	v_mov_b32_e32 v64, v0
	v_mov_b32_e32 v65, v0
	v_mov_b32_e32 v66, v0
	v_mov_b32_e32 v67, v0
	v_mov_b32_e32 v68, v0
	v_mov_b32_e32 v69, v0
	v_mov_b32_e32 v70, v0
	v_mov_b32_e32 v71, v0
	v_mov_b32_e32 v80, v0
	v_mov_b32_e32 v81, v0
	v_mov_b32_e32 v82, v0
	v_mov_b32_e32 v83, v0
	v_mov_b32_e32 v84, v0
	v_mov_b32_e32 v85, v0
	v_mov_b32_e32 v86, v0
	v_mov_b32_e32 v87, v0
	v_mov_b32_e32 v96, v0
	v_mov_b32_e32 v97, v0
	v_mov_b32_e32 v98, v0
	v_mov_b32_e32 v99, v0
	v_mov_b32_e32 v100, v0
	v_mov_b32_e32 v101, v0
	v_mov_b32_e32 v102, v0
	v_mov_b32_e32 v103, v0
	v_mov_b32_e32 v112, v0
	v_mov_b32_e32 v113, v0
	v_mov_b32_e32 v114, v0
	v_mov_b32_e32 v115, v0
	v_mov_b32_e32 v116, v0
	v_mov_b32_e32 v117, v0
	v_mov_b32_e32 v118, v0
	v_mov_b32_e32 v119, v0
	v_mov_b32_e32 v72, v0
	v_mov_b32_e32 v73, v0
	v_mov_b32_e32 v74, v0
	v_mov_b32_e32 v75, v0
	v_mov_b32_e32 v76, v0
	v_mov_b32_e32 v77, v0
	v_mov_b32_e32 v78, v0
	v_mov_b32_e32 v79, v0
	v_mov_b32_e32 v88, v0
	v_mov_b32_e32 v89, v0
	v_mov_b32_e32 v90, v0
	v_mov_b32_e32 v91, v0
	v_mov_b32_e32 v92, v0
	v_mov_b32_e32 v93, v0
	v_mov_b32_e32 v94, v0
	v_mov_b32_e32 v95, v0
	v_mov_b32_e32 v104, v0
	v_mov_b32_e32 v105, v0
	v_mov_b32_e32 v106, v0
	v_mov_b32_e32 v107, v0
	v_mov_b32_e32 v108, v0
	v_mov_b32_e32 v109, v0
	v_mov_b32_e32 v110, v0
	v_mov_b32_e32 v111, v0
	v_mov_b32_e32 v120, v0
	v_mov_b32_e32 v121, v0
	v_mov_b32_e32 v122, v0
	v_mov_b32_e32 v123, v0
	v_mov_b32_e32 v124, v0
	v_mov_b32_e32 v125, v0
	v_mov_b32_e32 v126, v0
	v_mov_b32_e32 v127, v0
	s_branch .LBB0_982

.LBB0_1033:
	s_add_u32 s35, s12, s48
	s_addc_u32 s36, s13, s49
	s_add_u32 s35, s35, 0x100
	s_addc_u32 s36, s36, 0
	s_add_u32 s37, s27, s48
	s_addc_u32 s43, s28, s49
	s_add_i32 s58, 0, 0x10000
	s_cmpk_eq_i32 s48, 0x700
	s_cselect_b32 s53, s29, s36
	s_cselect_b32 s52, s30, s35
	v_add_u32_e32 v147, s58, v144
	s_cselect_b32 s51, s19, s43
	s_cselect_b32 s50, s31, s37
	s_add_i32 s35, 0, 0x14000
	ds_read_b128 v[148:151], v147
	ds_read_b128 v[152:155], v147 offset:1024
	ds_read_b128 v[156:159], v147 offset:2048
	ds_read_b128 v[164:167], v147 offset:3072
	v_add_u32_e32 v147, s35, v144
	ds_read_b128 v[168:171], v147
	ds_read_b128 v[172:175], v147 offset:1024
	ds_read_b128 v[176:179], v147 offset:2048
	ds_read_b128 v[180:183], v147 offset:3072
	v_lshl_add_u64 v[236:237], v[138:139], 0, s[48:49]
	s_add_i32 m0, s7, 0xc000
	ds_read_b128 v[184:187], v145
	ds_read_b128 v[188:191], v145 offset:1024
	ds_read_b128 v[192:195], v145 offset:2048
	ds_read_b128 v[204:207], v145 offset:3072
	ds_read_b128 v[212:215], v145 offset:4096
	ds_read_b128 v[216:219], v145 offset:5120
	ds_read_b128 v[220:223], v145 offset:6144
	ds_read_b128 v[232:235], v145 offset:7168
	global_load_lds_dwordx4 v[236:237], off
	v_lshl_add_u64 v[236:237], v[140:141], 0, s[48:49]
	s_add_i32 m0, s7, 0xe000
	s_nop 0
	global_load_lds_dwordx4 v[236:237], off
	s_waitcnt vmcnt(8)
	s_cmp_eq_u32 s96, 0
	s_cbranch_scc1 .Lgl24
	s_waitcnt lgkmcnt(0)
.Lgl24:
	s_barrier
	s_waitcnt lgkmcnt(0)
	v_mfma_f32_16x16x32_bf16 v[76:79], v[148:151], v[184:187], v[76:79]
	v_mfma_f32_16x16x32_bf16 v[72:75], v[156:159], v[184:187], v[72:75]
	v_mfma_f32_16x16x32_bf16 v[116:119], v[148:151], v[192:195], v[116:119]
	v_mfma_f32_16x16x32_bf16 v[112:115], v[156:159], v[192:195], v[112:115]
	v_mfma_f32_16x16x32_bf16 v[88:91], v[148:151], v[212:215], v[88:91]
	v_mfma_f32_16x16x32_bf16 v[84:87], v[156:159], v[212:215], v[84:87]
	v_mfma_f32_16x16x32_bf16 v[108:111], v[148:151], v[220:223], v[108:111]
	v_mfma_f32_16x16x32_bf16 v[104:107], v[156:159], v[220:223], v[104:107]
	v_mfma_f32_16x16x32_bf16 v[76:79], v[152:155], v[188:191], v[76:79]
	v_mfma_f32_16x16x32_bf16 v[72:75], v[164:167], v[188:191], v[72:75]
	v_mfma_f32_16x16x32_bf16 v[116:119], v[152:155], v[204:207], v[116:119]
	v_mfma_f32_16x16x32_bf16 v[112:115], v[164:167], v[204:207], v[112:115]
	v_mfma_f32_16x16x32_bf16 v[88:91], v[152:155], v[216:219], v[88:91]
	v_mfma_f32_16x16x32_bf16 v[84:87], v[164:167], v[216:219], v[84:87]
	v_mfma_f32_16x16x32_bf16 v[108:111], v[152:155], v[232:235], v[108:111]
	v_mfma_f32_16x16x32_bf16 v[104:107], v[164:167], v[232:235], v[104:107]
	v_mfma_f32_16x16x32_bf16 v[96:99], v[168:171], v[184:187], v[96:99]
	v_mfma_f32_16x16x32_bf16 v[92:95], v[176:179], v[184:187], v[92:95]
	v_mfma_f32_16x16x32_bf16 v[124:127], v[168:171], v[192:195], v[124:127]
	v_mfma_f32_16x16x32_bf16 v[120:123], v[176:179], v[192:195], v[120:123]
	v_mfma_f32_16x16x32_bf16 v[100:103], v[168:171], v[212:215], v[100:103]
	v_mfma_f32_16x16x32_bf16 v[80:83], v[176:179], v[212:215], v[80:83]
	v_mfma_f32_16x16x32_bf16 v[68:71], v[168:171], v[220:223], v[68:71]
	v_mfma_f32_16x16x32_bf16 v[64:67], v[176:179], v[220:223], v[64:67]
	v_mfma_f32_16x16x32_bf16 v[96:99], v[172:175], v[188:191], v[96:99]
	v_mfma_f32_16x16x32_bf16 v[92:95], v[180:183], v[188:191], v[92:95]
	v_mfma_f32_16x16x32_bf16 v[124:127], v[172:175], v[204:207], v[124:127]
	v_mfma_f32_16x16x32_bf16 v[120:123], v[180:183], v[204:207], v[120:123]
	v_mfma_f32_16x16x32_bf16 v[100:103], v[172:175], v[216:219], v[100:103]
	v_mfma_f32_16x16x32_bf16 v[80:83], v[180:183], v[216:219], v[80:83]
	v_mfma_f32_16x16x32_bf16 v[68:71], v[172:175], v[232:235], v[68:71]
	v_mfma_f32_16x16x32_bf16 v[64:67], v[180:183], v[232:235], v[64:67]
	s_barrier
	s_add_i32 s36, s58, s9
	v_lshl_add_u64 v[236:237], s[50:51], 0, v[196:197]
	s_mov_b32 m0, s36
	ds_read_b128 v[184:187], v145 offset:16384
	ds_read_b128 v[188:191], v145 offset:17408
	ds_read_b128 v[192:195], v145 offset:18432
	ds_read_b128 v[204:207], v145 offset:19456
	ds_read_b128 v[212:215], v145 offset:20480
	ds_read_b128 v[216:219], v145 offset:21504
	ds_read_b128 v[220:223], v145 offset:22528
	ds_read_b128 v[232:235], v145 offset:23552
	global_load_lds_dwordx4 v[236:237], off
	s_add_i32 m0, s36, 0x2000
	s_add_u32 s36, s50, 0x40000
	v_lshl_add_u64 v[238:239], s[50:51], 0, v[132:133]
	s_addc_u32 s37, s51, 0
	s_add_i32 s35, s35, s9
	global_load_lds_dwordx4 v[238:239], off
	v_lshl_add_u64 v[240:241], s[36:37], 0, v[196:197]
	s_mov_b32 m0, s35
	v_lshl_add_u64 v[242:243], s[52:53], 0, v[130:131]
	global_load_lds_dwordx4 v[240:241], off
	v_lshl_add_u64 v[240:241], s[36:37], 0, v[132:133]
	s_add_i32 m0, s35, 0x2000
	s_nop 0
	global_load_lds_dwordx4 v[240:241], off
	v_lshl_add_u64 v[240:241], s[52:53], 0, v[128:129]
	s_mov_b32 m0, s7
	s_nop 0
	global_load_lds_dwordx4 v[240:241], off
	s_mov_b32 m0, s20
	s_nop 0
	global_load_lds_dwordx4 v[242:243], off
	s_waitcnt vmcnt(8)
	s_cmp_eq_u32 s96, 0
	s_cbranch_scc1 .Lgl25
	s_waitcnt lgkmcnt(0)
.Lgl25:
	s_barrier
	s_waitcnt lgkmcnt(0)
	v_mfma_f32_16x16x32_bf16 v[60:63], v[148:151], v[184:187], v[60:63]
	v_mfma_f32_16x16x32_bf16 v[56:59], v[156:159], v[184:187], v[56:59]
	v_mfma_f32_16x16x32_bf16 v[44:47], v[148:151], v[192:195], v[44:47]
	v_mfma_f32_16x16x32_bf16 v[40:43], v[156:159], v[192:195], v[40:43]
	v_mfma_f32_16x16x32_bf16 v[28:31], v[148:151], v[212:215], v[28:31]
	v_mfma_f32_16x16x32_bf16 v[24:27], v[156:159], v[212:215], v[24:27]
	v_mfma_f32_16x16x32_bf16 v[12:15], v[148:151], v[220:223], v[12:15]
	v_mfma_f32_16x16x32_bf16 v[8:11], v[156:159], v[220:223], v[8:11]
	v_mfma_f32_16x16x32_bf16 v[60:63], v[152:155], v[188:191], v[60:63]
	v_mfma_f32_16x16x32_bf16 v[56:59], v[164:167], v[188:191], v[56:59]
	v_mfma_f32_16x16x32_bf16 v[44:47], v[152:155], v[204:207], v[44:47]
	v_mfma_f32_16x16x32_bf16 v[40:43], v[164:167], v[204:207], v[40:43]
	v_mfma_f32_16x16x32_bf16 v[28:31], v[152:155], v[216:219], v[28:31]
	v_mfma_f32_16x16x32_bf16 v[24:27], v[164:167], v[216:219], v[24:27]
	v_mfma_f32_16x16x32_bf16 v[12:15], v[152:155], v[232:235], v[12:15]
	v_mfma_f32_16x16x32_bf16 v[8:11], v[164:167], v[232:235], v[8:11]
	v_mfma_f32_16x16x32_bf16 v[52:55], v[168:171], v[184:187], v[52:55]
	v_mfma_f32_16x16x32_bf16 v[48:51], v[176:179], v[184:187], v[48:51]
	v_mfma_f32_16x16x32_bf16 v[36:39], v[168:171], v[192:195], v[36:39]
	v_mfma_f32_16x16x32_bf16 v[32:35], v[176:179], v[192:195], v[32:35]
	v_mfma_f32_16x16x32_bf16 v[20:23], v[168:171], v[212:215], v[20:23]
	v_mfma_f32_16x16x32_bf16 v[16:19], v[176:179], v[212:215], v[16:19]
	v_mfma_f32_16x16x32_bf16 v[4:7], v[168:171], v[220:223], v[4:7]
	v_mfma_f32_16x16x32_bf16 v[0:3], v[176:179], v[220:223], v[0:3]
	v_mfma_f32_16x16x32_bf16 v[52:55], v[172:175], v[188:191], v[52:55]
	v_mfma_f32_16x16x32_bf16 v[48:51], v[180:183], v[188:191], v[48:51]
	v_mfma_f32_16x16x32_bf16 v[36:39], v[172:175], v[204:207], v[36:39]
	v_mfma_f32_16x16x32_bf16 v[32:35], v[180:183], v[204:207], v[32:35]
	v_mfma_f32_16x16x32_bf16 v[20:23], v[172:175], v[216:219], v[20:23]
	v_mfma_f32_16x16x32_bf16 v[16:19], v[180:183], v[216:219], v[16:19]
	v_mfma_f32_16x16x32_bf16 v[4:7], v[172:175], v[232:235], v[4:7]
	v_mfma_f32_16x16x32_bf16 v[0:3], v[180:183], v[232:235], v[0:3]
	s_barrier
	s_add_i32 s35, 0, 0x18000
	v_add_u32_e32 v147, s35, v144
	s_add_i32 s43, 0, 0x1c000
	ds_read_b128 v[148:151], v147
	ds_read_b128 v[152:155], v147 offset:1024
	ds_read_b128 v[156:159], v147 offset:2048
	ds_read_b128 v[164:167], v147 offset:3072
	v_add_u32_e32 v147, s43, v144
	ds_read_b128 v[168:171], v147
	ds_read_b128 v[172:175], v147 offset:1024
	ds_read_b128 v[176:179], v147 offset:2048
	ds_read_b128 v[180:183], v147 offset:3072
	s_add_u32 s36, s52, 0x40000
	s_addc_u32 s37, s53, 0
	s_mov_b32 m0, s21
	v_lshl_add_u64 v[244:245], s[36:37], 0, v[128:129]
	ds_read_b128 v[184:187], v145 offset:32768
	ds_read_b128 v[188:191], v145 offset:33792
	ds_read_b128 v[192:195], v145 offset:34816
	ds_read_b128 v[204:207], v145 offset:35840
	ds_read_b128 v[212:215], v145 offset:36864
	ds_read_b128 v[216:219], v145 offset:37888
	ds_read_b128 v[220:223], v145 offset:38912
	ds_read_b128 v[232:235], v145 offset:39936
	global_load_lds_dwordx4 v[244:245], off
	v_lshl_add_u64 v[244:245], s[36:37], 0, v[130:131]
	s_mov_b32 m0, s22
	s_nop 0
	global_load_lds_dwordx4 v[244:245], off
	s_waitcnt vmcnt(8)
	s_cmp_eq_u32 s96, 0
	s_cbranch_scc1 .Lgl26
	s_waitcnt lgkmcnt(0)
.Lgl26:
	s_barrier
	s_waitcnt lgkmcnt(0)
	v_mfma_f32_16x16x32_bf16 v[76:79], v[148:151], v[184:187], v[76:79]
	v_mfma_f32_16x16x32_bf16 v[72:75], v[156:159], v[184:187], v[72:75]
	v_mfma_f32_16x16x32_bf16 v[116:119], v[148:151], v[192:195], v[116:119]
	v_mfma_f32_16x16x32_bf16 v[112:115], v[156:159], v[192:195], v[112:115]
	v_mfma_f32_16x16x32_bf16 v[88:91], v[148:151], v[212:215], v[88:91]
	v_mfma_f32_16x16x32_bf16 v[84:87], v[156:159], v[212:215], v[84:87]
	v_mfma_f32_16x16x32_bf16 v[108:111], v[148:151], v[220:223], v[108:111]
	v_mfma_f32_16x16x32_bf16 v[104:107], v[156:159], v[220:223], v[104:107]
	v_mfma_f32_16x16x32_bf16 v[76:79], v[152:155], v[188:191], v[76:79]
	v_mfma_f32_16x16x32_bf16 v[72:75], v[164:167], v[188:191], v[72:75]
	v_mfma_f32_16x16x32_bf16 v[116:119], v[152:155], v[204:207], v[116:119]
	v_mfma_f32_16x16x32_bf16 v[112:115], v[164:167], v[204:207], v[112:115]
	v_mfma_f32_16x16x32_bf16 v[88:91], v[152:155], v[216:219], v[88:91]
	v_mfma_f32_16x16x32_bf16 v[84:87], v[164:167], v[216:219], v[84:87]
	v_mfma_f32_16x16x32_bf16 v[108:111], v[152:155], v[232:235], v[108:111]
	v_mfma_f32_16x16x32_bf16 v[104:107], v[164:167], v[232:235], v[104:107]
	v_mfma_f32_16x16x32_bf16 v[96:99], v[168:171], v[184:187], v[96:99]
	v_mfma_f32_16x16x32_bf16 v[92:95], v[176:179], v[184:187], v[92:95]
	v_mfma_f32_16x16x32_bf16 v[124:127], v[168:171], v[192:195], v[124:127]
	v_mfma_f32_16x16x32_bf16 v[120:123], v[176:179], v[192:195], v[120:123]
	v_mfma_f32_16x16x32_bf16 v[100:103], v[168:171], v[212:215], v[100:103]
	v_mfma_f32_16x16x32_bf16 v[80:83], v[176:179], v[212:215], v[80:83]
	v_mfma_f32_16x16x32_bf16 v[68:71], v[168:171], v[220:223], v[68:71]
	v_mfma_f32_16x16x32_bf16 v[64:67], v[176:179], v[220:223], v[64:67]
	v_mfma_f32_16x16x32_bf16 v[96:99], v[172:175], v[188:191], v[96:99]
	v_mfma_f32_16x16x32_bf16 v[92:95], v[180:183], v[188:191], v[92:95]
	v_mfma_f32_16x16x32_bf16 v[124:127], v[172:175], v[204:207], v[124:127]
	v_mfma_f32_16x16x32_bf16 v[120:123], v[180:183], v[204:207], v[120:123]
	v_mfma_f32_16x16x32_bf16 v[100:103], v[172:175], v[216:219], v[100:103]
	v_mfma_f32_16x16x32_bf16 v[80:83], v[180:183], v[216:219], v[80:83]
	v_mfma_f32_16x16x32_bf16 v[68:71], v[172:175], v[232:235], v[68:71]
	v_mfma_f32_16x16x32_bf16 v[64:67], v[180:183], v[232:235], v[64:67]
	s_barrier
	s_add_i32 s35, s35, s9
	v_lshl_add_u64 v[236:237], v[236:237], 0, s[10:11]
	s_mov_b32 m0, s35
	ds_read_b128 v[184:187], v145 offset:49152
	ds_read_b128 v[188:191], v145 offset:50176
	ds_read_b128 v[192:195], v145 offset:51200
	ds_read_b128 v[204:207], v145 offset:52224
	ds_read_b128 v[212:215], v145 offset:53248
	ds_read_b128 v[216:219], v145 offset:54272
	ds_read_b128 v[220:223], v145 offset:55296
	ds_read_b128 v[232:235], v145 offset:56320
	global_load_lds_dwordx4 v[236:237], off
	s_add_i32 m0, s35, 0x2000
	s_add_u32 s36, s50, 0x40080
	v_lshl_add_u64 v[236:237], v[238:239], 0, s[10:11]
	s_addc_u32 s37, s51, 0
	s_add_i32 s35, s43, s9
	global_load_lds_dwordx4 v[236:237], off
	v_lshl_add_u64 v[236:237], s[36:37], 0, v[196:197]
	s_mov_b32 m0, s35
	s_nop 0
	global_load_lds_dwordx4 v[236:237], off
	v_lshl_add_u64 v[236:237], s[36:37], 0, v[132:133]
	s_add_i32 m0, s35, 0x2000
	s_nop 0
	global_load_lds_dwordx4 v[236:237], off
	v_lshl_add_u64 v[236:237], v[240:241], 0, s[10:11]
	s_mov_b32 m0, s23
	s_nop 0
	global_load_lds_dwordx4 v[236:237], off
	v_lshl_add_u64 v[236:237], v[242:243], 0, s[10:11]
	s_mov_b32 m0, s24
	s_nop 0
	global_load_lds_dwordx4 v[236:237], off
	s_waitcnt vmcnt(8)
	s_cmp_eq_u32 s96, 0
	s_cbranch_scc1 .Lgl27
	s_waitcnt lgkmcnt(0)
.Lgl27:
	s_barrier
	s_waitcnt lgkmcnt(0)
	v_mfma_f32_16x16x32_bf16 v[60:63], v[148:151], v[184:187], v[60:63]
	v_mfma_f32_16x16x32_bf16 v[56:59], v[156:159], v[184:187], v[56:59]
	v_mfma_f32_16x16x32_bf16 v[44:47], v[148:151], v[192:195], v[44:47]
	v_mfma_f32_16x16x32_bf16 v[40:43], v[156:159], v[192:195], v[40:43]
	v_mfma_f32_16x16x32_bf16 v[28:31], v[148:151], v[212:215], v[28:31]
	v_mfma_f32_16x16x32_bf16 v[24:27], v[156:159], v[212:215], v[24:27]
	v_mfma_f32_16x16x32_bf16 v[12:15], v[148:151], v[220:223], v[12:15]
	v_mfma_f32_16x16x32_bf16 v[8:11], v[156:159], v[220:223], v[8:11]
	v_mfma_f32_16x16x32_bf16 v[60:63], v[152:155], v[188:191], v[60:63]
	v_mfma_f32_16x16x32_bf16 v[56:59], v[164:167], v[188:191], v[56:59]
	v_mfma_f32_16x16x32_bf16 v[44:47], v[152:155], v[204:207], v[44:47]
	v_mfma_f32_16x16x32_bf16 v[40:43], v[164:167], v[204:207], v[40:43]
	v_mfma_f32_16x16x32_bf16 v[28:31], v[152:155], v[216:219], v[28:31]
	v_mfma_f32_16x16x32_bf16 v[24:27], v[164:167], v[216:219], v[24:27]
	v_mfma_f32_16x16x32_bf16 v[12:15], v[152:155], v[232:235], v[12:15]
	v_mfma_f32_16x16x32_bf16 v[8:11], v[164:167], v[232:235], v[8:11]
	v_mfma_f32_16x16x32_bf16 v[52:55], v[168:171], v[184:187], v[52:55]
	v_mfma_f32_16x16x32_bf16 v[48:51], v[176:179], v[184:187], v[48:51]
	v_mfma_f32_16x16x32_bf16 v[36:39], v[168:171], v[192:195], v[36:39]
	v_mfma_f32_16x16x32_bf16 v[32:35], v[176:179], v[192:195], v[32:35]
	v_mfma_f32_16x16x32_bf16 v[20:23], v[168:171], v[212:215], v[20:23]
	v_mfma_f32_16x16x32_bf16 v[16:19], v[176:179], v[212:215], v[16:19]
	v_mfma_f32_16x16x32_bf16 v[4:7], v[168:171], v[220:223], v[4:7]
	v_mfma_f32_16x16x32_bf16 v[0:3], v[176:179], v[220:223], v[0:3]
	v_mfma_f32_16x16x32_bf16 v[52:55], v[172:175], v[188:191], v[52:55]
	v_mfma_f32_16x16x32_bf16 v[48:51], v[180:183], v[188:191], v[48:51]
	v_mfma_f32_16x16x32_bf16 v[36:39], v[172:175], v[204:207], v[36:39]
	v_mfma_f32_16x16x32_bf16 v[32:35], v[180:183], v[204:207], v[32:35]
	v_mfma_f32_16x16x32_bf16 v[20:23], v[172:175], v[216:219], v[20:23]
	v_mfma_f32_16x16x32_bf16 v[16:19], v[180:183], v[216:219], v[16:19]
	v_mfma_f32_16x16x32_bf16 v[4:7], v[172:175], v[232:235], v[4:7]
	v_mfma_f32_16x16x32_bf16 v[0:3], v[180:183], v[232:235], v[0:3]
	s_barrier
	s_add_i32 s34, s34, 2
	s_add_u32 s48, s48, 0x100
	s_addc_u32 s49, s49, 0
	s_cmp_gt_u32 s34, 13
	s_cbranch_scc0 .LBB0_1033
	s_add_u32 s48, s27, 0xffffff00
	s_addc_u32 s49, s28, -1
	s_andn2_b64 vcc, exec, s[40:41]
	s_cbranch_vccnz .LBB0_1036
	v_mov_b32_e32 v0, 0
	s_mov_b32 s8, s18
	s_mov_b32 s6, s42
	s_mov_b64 s[12:13], s[46:47]
	s_mov_b32 s25, s26
	v_mov_b32_e32 v1, v0
	v_mov_b32_e32 v2, v0
	v_mov_b32_e32 v3, v0
	v_mov_b32_e32 v4, v0
	v_mov_b32_e32 v5, v0
	v_mov_b32_e32 v6, v0
	v_mov_b32_e32 v7, v0
	v_mov_b32_e32 v16, v0
	v_mov_b32_e32 v17, v0
	v_mov_b32_e32 v18, v0
	v_mov_b32_e32 v19, v0
	v_mov_b32_e32 v20, v0
	v_mov_b32_e32 v21, v0
	v_mov_b32_e32 v22, v0
	v_mov_b32_e32 v23, v0
	v_mov_b32_e32 v32, v0
	v_mov_b32_e32 v33, v0
	v_mov_b32_e32 v34, v0
	v_mov_b32_e32 v35, v0
	v_mov_b32_e32 v36, v0
	v_mov_b32_e32 v37, v0
	v_mov_b32_e32 v38, v0
	v_mov_b32_e32 v39, v0
	v_mov_b32_e32 v48, v0
	v_mov_b32_e32 v49, v0
	v_mov_b32_e32 v50, v0
	v_mov_b32_e32 v51, v0
	v_mov_b32_e32 v52, v0
	v_mov_b32_e32 v53, v0
	v_mov_b32_e32 v54, v0
	v_mov_b32_e32 v55, v0
	v_mov_b32_e32 v8, v0
	v_mov_b32_e32 v9, v0
	v_mov_b32_e32 v10, v0
	v_mov_b32_e32 v11, v0
	v_mov_b32_e32 v12, v0
	v_mov_b32_e32 v13, v0
	v_mov_b32_e32 v14, v0
	v_mov_b32_e32 v15, v0
	v_mov_b32_e32 v24, v0
	v_mov_b32_e32 v25, v0
	v_mov_b32_e32 v26, v0
	v_mov_b32_e32 v27, v0
	v_mov_b32_e32 v28, v0
	v_mov_b32_e32 v29, v0
	v_mov_b32_e32 v30, v0
	v_mov_b32_e32 v31, v0
	v_mov_b32_e32 v40, v0
	v_mov_b32_e32 v41, v0
	v_mov_b32_e32 v42, v0
	v_mov_b32_e32 v43, v0
	v_mov_b32_e32 v44, v0
	v_mov_b32_e32 v45, v0
	v_mov_b32_e32 v46, v0
	v_mov_b32_e32 v47, v0
	v_mov_b32_e32 v56, v0
	v_mov_b32_e32 v57, v0
	v_mov_b32_e32 v58, v0
	v_mov_b32_e32 v59, v0
	v_mov_b32_e32 v60, v0
	v_mov_b32_e32 v61, v0
	v_mov_b32_e32 v62, v0
	v_mov_b32_e32 v63, v0
	v_mov_b32_e32 v64, v0
	v_mov_b32_e32 v65, v0
	v_mov_b32_e32 v66, v0
	v_mov_b32_e32 v67, v0
	v_mov_b32_e32 v68, v0
	v_mov_b32_e32 v69, v0
	v_mov_b32_e32 v70, v0
	v_mov_b32_e32 v71, v0
	v_mov_b32_e32 v80, v0
	v_mov_b32_e32 v81, v0
	v_mov_b32_e32 v82, v0
	v_mov_b32_e32 v83, v0
	v_mov_b32_e32 v100, v0
	v_mov_b32_e32 v101, v0
	v_mov_b32_e32 v102, v0
	v_mov_b32_e32 v103, v0
	v_mov_b32_e32 v120, v0
	v_mov_b32_e32 v121, v0
	v_mov_b32_e32 v122, v0
	v_mov_b32_e32 v123, v0
	v_mov_b32_e32 v124, v0
	v_mov_b32_e32 v125, v0
	v_mov_b32_e32 v126, v0
	v_mov_b32_e32 v127, v0
	v_mov_b32_e32 v92, v0
	v_mov_b32_e32 v93, v0
	v_mov_b32_e32 v94, v0
	v_mov_b32_e32 v95, v0
	v_mov_b32_e32 v96, v0
	v_mov_b32_e32 v97, v0
	v_mov_b32_e32 v98, v0
	v_mov_b32_e32 v99, v0
	v_mov_b32_e32 v104, v0
	v_mov_b32_e32 v105, v0
	v_mov_b32_e32 v106, v0
	v_mov_b32_e32 v107, v0
	v_mov_b32_e32 v108, v0
	v_mov_b32_e32 v109, v0
	v_mov_b32_e32 v110, v0
	v_mov_b32_e32 v111, v0
	v_mov_b32_e32 v84, v0
	v_mov_b32_e32 v85, v0
	v_mov_b32_e32 v86, v0
	v_mov_b32_e32 v87, v0
	v_mov_b32_e32 v88, v0
	v_mov_b32_e32 v89, v0
	v_mov_b32_e32 v90, v0
	v_mov_b32_e32 v91, v0
	v_mov_b32_e32 v112, v0
	v_mov_b32_e32 v113, v0
	v_mov_b32_e32 v114, v0
	v_mov_b32_e32 v115, v0
	v_mov_b32_e32 v116, v0
	v_mov_b32_e32 v117, v0
	v_mov_b32_e32 v118, v0
	v_mov_b32_e32 v119, v0
	v_mov_b32_e32 v72, v0
	v_mov_b32_e32 v73, v0
	v_mov_b32_e32 v74, v0
	v_mov_b32_e32 v75, v0
	v_mov_b32_e32 v76, v0
	v_mov_b32_e32 v77, v0
	v_mov_b32_e32 v78, v0
	v_mov_b32_e32 v79, v0
	s_branch .LBB0_1037
